# best_final + P0 weight-copy loops: bf16 rounding bit trick -> v_cvt_pk_bf16_f32 (144 pairs), with store-data wait states after the dwordx4 stores
# baseline (speedup 1.0000x reference)
.LBB0_87:
	s_lshl_b32 s4, s7, 6
	v_or_b32_e32 v2, s4, v16
	s_ashr_i32 s7, s6, 31
	v_lshl_add_u64 v[30:31], s[6:7], 2, v[12:13]
	v_or_b32_e32 v34, 2, v2
	v_or_b32_e32 v36, 4, v2
	v_or_b32_e32 v38, 6, v2
	v_or_b32_e32 v40, 8, v2
	v_or_b32_e32 v42, 10, v2
	v_or_b32_e32 v44, 12, v2
	v_or_b32_e32 v46, 14, v2
	v_mad_i64_i32 v[32:33], s[6:7], v2, s28, v[30:31]
	v_mad_i64_i32 v[34:35], s[6:7], v34, s28, v[30:31]
	v_mad_i64_i32 v[36:37], s[6:7], v36, s28, v[30:31]
	v_mad_i64_i32 v[38:39], s[6:7], v38, s28, v[30:31]
	v_mad_i64_i32 v[40:41], s[6:7], v40, s28, v[30:31]
	v_mad_i64_i32 v[42:43], s[6:7], v42, s28, v[30:31]
	v_mad_i64_i32 v[44:45], s[6:7], v44, s28, v[30:31]
	v_mad_i64_i32 v[46:47], s[6:7], v46, s28, v[30:31]
	global_load_dword v48, v[32:33], off
	global_load_dword v49, v[34:35], off
	global_load_dword v50, v[36:37], off
	global_load_dword v51, v[38:39], off
	global_load_dword v52, v[40:41], off
	global_load_dword v53, v[42:43], off
	global_load_dword v54, v[44:45], off
	global_load_dword v55, v[46:47], off
	v_or_b32_e32 v32, 16, v2
	v_or_b32_e32 v34, 18, v2
	v_or_b32_e32 v36, 20, v2
	v_or_b32_e32 v38, 22, v2
	v_or_b32_e32 v40, 24, v2
	v_or_b32_e32 v42, 26, v2
	v_or_b32_e32 v44, 28, v2
	v_or_b32_e32 v46, 30, v2
	v_mad_i64_i32 v[32:33], s[6:7], v32, s28, v[30:31]
	v_mad_i64_i32 v[34:35], s[6:7], v34, s28, v[30:31]
	v_mad_i64_i32 v[36:37], s[6:7], v36, s28, v[30:31]
	v_mad_i64_i32 v[38:39], s[6:7], v38, s28, v[30:31]
	v_mad_i64_i32 v[40:41], s[6:7], v40, s28, v[30:31]
	v_mad_i64_i32 v[42:43], s[6:7], v42, s28, v[30:31]
	v_mad_i64_i32 v[44:45], s[6:7], v44, s28, v[30:31]
	v_mad_i64_i32 v[46:47], s[6:7], v46, s28, v[30:31]
	global_load_dword v56, v[32:33], off
	global_load_dword v57, v[34:35], off
	global_load_dword v58, v[36:37], off
	global_load_dword v59, v[38:39], off
	global_load_dword v60, v[40:41], off
	global_load_dword v61, v[42:43], off
	global_load_dword v62, v[44:45], off
	global_load_dword v63, v[46:47], off
	v_or_b32_e32 v32, 32, v2
	v_or_b32_e32 v34, 34, v2
	v_or_b32_e32 v36, 36, v2
	v_or_b32_e32 v38, 38, v2
	v_or_b32_e32 v40, 40, v2
	v_or_b32_e32 v42, 42, v2
	v_or_b32_e32 v44, 44, v2
	v_or_b32_e32 v46, 46, v2
	v_mad_i64_i32 v[32:33], s[6:7], v32, s28, v[30:31]
	v_mad_i64_i32 v[34:35], s[6:7], v34, s28, v[30:31]
	v_mad_i64_i32 v[36:37], s[6:7], v36, s28, v[30:31]
	v_mad_i64_i32 v[38:39], s[6:7], v38, s28, v[30:31]
	v_mad_i64_i32 v[40:41], s[6:7], v40, s28, v[30:31]
	v_mad_i64_i32 v[42:43], s[6:7], v42, s28, v[30:31]
	v_mad_i64_i32 v[44:45], s[6:7], v44, s28, v[30:31]
	v_mad_i64_i32 v[46:47], s[6:7], v46, s28, v[30:31]
	global_load_dword v64, v[32:33], off
	global_load_dword v65, v[34:35], off
	global_load_dword v66, v[36:37], off
	global_load_dword v67, v[38:39], off
	global_load_dword v68, v[40:41], off
	global_load_dword v69, v[42:43], off
	global_load_dword v70, v[44:45], off
	s_nop 0
	global_load_dword v46, v[46:47], off
	v_or_b32_e32 v32, 48, v2
	v_or_b32_e32 v34, 50, v2
	v_or_b32_e32 v36, 52, v2
	v_or_b32_e32 v38, 54, v2
	v_or_b32_e32 v40, 56, v2
	v_or_b32_e32 v42, 58, v2
	v_or_b32_e32 v44, 60, v2
	v_or_b32_e32 v2, 62, v2
	v_mad_i64_i32 v[32:33], s[6:7], v32, s28, v[30:31]
	v_mad_i64_i32 v[34:35], s[6:7], v34, s28, v[30:31]
	v_mad_i64_i32 v[36:37], s[6:7], v36, s28, v[30:31]
	v_mad_i64_i32 v[38:39], s[6:7], v38, s28, v[30:31]
	v_mad_i64_i32 v[40:41], s[6:7], v40, s28, v[30:31]
	v_mad_i64_i32 v[42:43], s[6:7], v42, s28, v[30:31]
	v_mad_i64_i32 v[44:45], s[6:7], v44, s28, v[30:31]
	v_mad_i64_i32 v[30:31], s[6:7], v2, s28, v[30:31]
	global_load_dword v2, v[32:33], off
	s_nop 0
	global_load_dword v32, v[34:35], off
	global_load_dword v33, v[36:37], off
	s_nop 0
	global_load_dword v34, v[38:39], off
	global_load_dword v35, v[40:41], off
	global_load_dword v36, v[42:43], off
	global_load_dword v37, v[44:45], off
	s_nop 0
	global_load_dword v30, v[30:31], off
	s_waitcnt vmcnt(30)
	ds_write2_b32 v17, v48, v49 offset1:66
	s_waitcnt vmcnt(28)
	ds_write2_b32 v17, v50, v51 offset0:132 offset1:198
	s_waitcnt vmcnt(26)
	ds_write2_b32 v23, v52, v53 offset0:8 offset1:74
	s_waitcnt vmcnt(24)
	ds_write2_b32 v23, v54, v55 offset0:140 offset1:206
	s_waitcnt vmcnt(22)
	ds_write2_b32 v24, v56, v57 offset0:16 offset1:82
	s_waitcnt vmcnt(20)
	ds_write2_b32 v24, v58, v59 offset0:148 offset1:214
	s_waitcnt vmcnt(18)
	ds_write2_b32 v25, v60, v61 offset0:24 offset1:90
	s_waitcnt vmcnt(16)
	ds_write2_b32 v25, v62, v63 offset0:156 offset1:222
	s_waitcnt vmcnt(14)
	ds_write2_b32 v26, v64, v65 offset0:32 offset1:98
	s_waitcnt vmcnt(12)
	ds_write2_b32 v26, v66, v67 offset0:164 offset1:230
	s_waitcnt vmcnt(10)
	ds_write2_b32 v27, v68, v69 offset0:40 offset1:106
	s_waitcnt vmcnt(8)
	ds_write2_b32 v27, v70, v46 offset0:172 offset1:238
	s_waitcnt vmcnt(6)
	ds_write2_b32 v28, v2, v32 offset0:48 offset1:114
	s_waitcnt vmcnt(4)
	ds_write2_b32 v28, v33, v34 offset0:180 offset1:246
	s_waitcnt vmcnt(2)
	ds_write2_b32 v29, v35, v36 offset0:56 offset1:122
	s_waitcnt vmcnt(0)
	ds_write2_b32 v29, v37, v30 offset0:188 offset1:254
	s_waitcnt lgkmcnt(0)
	ds_read2_b32 v[34:35], v19 offset1:8
	ds_read2_b32 v[38:39], v19 offset0:33 offset1:41
	ds_read2_b32 v[40:41], v19 offset0:66 offset1:74
	ds_read2_b32 v[42:43], v19 offset0:99 offset1:107
	ds_read2_b32 v[44:45], v19 offset0:132 offset1:140
	s_waitcnt lgkmcnt(4)
	s_waitcnt lgkmcnt(3)
	ds_read2_b32 v[46:47], v19 offset0:165 offset1:173
	v_cvt_pk_bf16_f32 v30, v34, v38
	s_waitcnt lgkmcnt(3)
	s_waitcnt lgkmcnt(2)
	ds_read2_b32 v[48:49], v19 offset0:198 offset1:206
	ds_read2_b32 v[50:51], v19 offset0:231 offset1:239
	v_cvt_pk_bf16_f32 v31, v40, v42
	s_waitcnt lgkmcnt(3)
	s_waitcnt lgkmcnt(2)
	v_cvt_pk_bf16_f32 v32, v44, v46
	s_waitcnt lgkmcnt(1)
	v_add_u32_e32 v52, s0, v18
	s_ashr_i32 s5, s4, 31
	s_waitcnt lgkmcnt(0)
	v_ashrrev_i32_e32 v53, 31, v52
	v_lshl_add_u64 v[36:37], s[4:5], 1, v[14:15]
	v_lshlrev_b64 v[52:53], 11, v[52:53]
	v_cvt_pk_bf16_f32 v33, v48, v50
	v_lshl_add_u64 v[52:53], v[36:37], 0, v[52:53]
	global_store_dwordx4 v[52:53], v[30:33], off
	s_nop 1
	v_cvt_pk_bf16_f32 v30, v35, v39
	v_cvt_pk_bf16_f32 v31, v41, v43
	v_cvt_pk_bf16_f32 v32, v45, v47
	v_add_u32_e32 v34, s0, v20
	v_ashrrev_i32_e32 v35, 31, v34
	v_lshlrev_b64 v[34:35], 11, v[34:35]
	v_cvt_pk_bf16_f32 v33, v49, v51
	ds_read2_b32 v[38:39], v19 offset0:16 offset1:24
	v_lshl_add_u64 v[34:35], v[36:37], 0, v[34:35]
	global_store_dwordx4 v[34:35], v[30:33], off
	s_nop 1
	ds_read2_b32 v[34:35], v19 offset0:49 offset1:57
	ds_read2_b32 v[40:41], v19 offset0:82 offset1:90
	ds_read2_b32 v[42:43], v19 offset0:115 offset1:123
	s_waitcnt lgkmcnt(3)
	s_waitcnt lgkmcnt(2)
	ds_read2_b32 v[44:45], v19 offset0:148 offset1:156
	ds_read2_b32 v[46:47], v19 offset0:181 offset1:189
	v_cvt_pk_bf16_f32 v30, v38, v34
	s_waitcnt lgkmcnt(3)
	s_waitcnt lgkmcnt(2)
	ds_read2_b32 v[48:49], v19 offset0:214 offset1:222
	ds_read2_b32 v[50:51], v19 offset0:247 offset1:255
	v_cvt_pk_bf16_f32 v31, v40, v42
	s_waitcnt lgkmcnt(3)
	s_waitcnt lgkmcnt(2)
	v_cvt_pk_bf16_f32 v32, v44, v46
	s_waitcnt lgkmcnt(1)
	v_add_u32_e32 v52, s0, v21
	s_waitcnt lgkmcnt(0)
	v_ashrrev_i32_e32 v53, 31, v52
	v_lshlrev_b64 v[52:53], 11, v[52:53]
	v_cvt_pk_bf16_f32 v33, v48, v50
	v_lshl_add_u64 v[52:53], v[36:37], 0, v[52:53]
	global_store_dwordx4 v[52:53], v[30:33], off
	s_nop 1
	v_cvt_pk_bf16_f32 v30, v39, v35
	v_cvt_pk_bf16_f32 v31, v41, v43
	v_cvt_pk_bf16_f32 v32, v45, v47
	v_add_u32_e32 v34, s0, v22
	v_ashrrev_i32_e32 v35, 31, v34
	v_lshlrev_b64 v[34:35], 11, v[34:35]
	v_cvt_pk_bf16_f32 v33, v49, v51
	v_lshl_add_u64 v[34:35], v[36:37], 0, v[34:35]
	global_store_dwordx4 v[34:35], v[30:33], off
	s_nop 1
	s_waitcnt lgkmcnt(0)

.LBB0_89:
	s_cmpk_gt_i32 s29, 0xaff
	s_mov_b64 s[4:5], -1
	s_cbranch_scc0 .LBB0_99
	s_cmpk_gt_u32 s29, 0x15ff
	s_cbranch_scc0 .LBB0_92
	s_and_b32 s5, s14, 0x7fffffc0
	s_and_b32 s4, s10, 0x3e0
	v_or_b32_e32 v2, s5, v16
	s_lshl_b32 s0, s4, 2
	v_or_b32_e32 v34, 2, v2
	v_mov_b32_e32 v35, v3
	v_or_b32_e32 v36, 4, v2
	v_mov_b32_e32 v37, v3
	v_or_b32_e32 v38, 6, v2
	v_mov_b32_e32 v39, v3
	v_or_b32_e32 v40, 8, v2
	v_mov_b32_e32 v41, v3
	v_or_b32_e32 v42, 10, v2
	v_mov_b32_e32 v43, v3
	v_or_b32_e32 v44, 12, v2
	v_mov_b32_e32 v45, v3
	v_lshl_add_u64 v[30:31], v[4:5], 0, s[0:1]
	v_lshlrev_b64 v[32:33], 12, v[2:3]
	v_lshlrev_b64 v[34:35], 12, v[34:35]
	v_lshlrev_b64 v[36:37], 12, v[36:37]
	v_lshlrev_b64 v[38:39], 12, v[38:39]
	v_lshlrev_b64 v[40:41], 12, v[40:41]
	v_lshlrev_b64 v[42:43], 12, v[42:43]
	v_lshlrev_b64 v[44:45], 12, v[44:45]
	v_or_b32_e32 v46, 14, v2
	v_mov_b32_e32 v47, v3
	v_lshl_add_u64 v[32:33], v[30:31], 0, v[32:33]
	v_lshl_add_u64 v[34:35], v[30:31], 0, v[34:35]
	v_lshl_add_u64 v[36:37], v[30:31], 0, v[36:37]
	v_lshl_add_u64 v[38:39], v[30:31], 0, v[38:39]
	v_lshl_add_u64 v[40:41], v[30:31], 0, v[40:41]
	v_lshl_add_u64 v[42:43], v[30:31], 0, v[42:43]
	v_lshl_add_u64 v[44:45], v[30:31], 0, v[44:45]
	v_lshlrev_b64 v[46:47], 12, v[46:47]
	v_lshl_add_u64 v[46:47], v[30:31], 0, v[46:47]
	global_load_dword v48, v[32:33], off
	global_load_dword v49, v[34:35], off
	global_load_dword v50, v[36:37], off
	global_load_dword v51, v[38:39], off
	global_load_dword v52, v[40:41], off
	global_load_dword v53, v[42:43], off
	global_load_dword v54, v[44:45], off
	global_load_dword v55, v[46:47], off
	v_or_b32_e32 v32, 16, v2
	v_mov_b32_e32 v33, v3
	v_or_b32_e32 v34, 18, v2
	v_mov_b32_e32 v35, v3
	v_or_b32_e32 v36, 20, v2
	v_mov_b32_e32 v37, v3
	v_or_b32_e32 v38, 22, v2
	v_mov_b32_e32 v39, v3
	v_or_b32_e32 v40, 24, v2
	v_mov_b32_e32 v41, v3
	v_or_b32_e32 v42, 26, v2
	v_mov_b32_e32 v43, v3
	v_or_b32_e32 v44, 28, v2
	v_mov_b32_e32 v45, v3
	v_lshlrev_b64 v[32:33], 12, v[32:33]
	v_lshlrev_b64 v[34:35], 12, v[34:35]
	v_lshlrev_b64 v[36:37], 12, v[36:37]
	v_lshlrev_b64 v[38:39], 12, v[38:39]
	v_lshlrev_b64 v[40:41], 12, v[40:41]
	v_lshlrev_b64 v[42:43], 12, v[42:43]
	v_lshlrev_b64 v[44:45], 12, v[44:45]
	v_or_b32_e32 v46, 30, v2
	v_mov_b32_e32 v47, v3
	v_lshl_add_u64 v[32:33], v[30:31], 0, v[32:33]
	v_lshl_add_u64 v[34:35], v[30:31], 0, v[34:35]
	v_lshl_add_u64 v[36:37], v[30:31], 0, v[36:37]
	v_lshl_add_u64 v[38:39], v[30:31], 0, v[38:39]
	v_lshl_add_u64 v[40:41], v[30:31], 0, v[40:41]
	v_lshl_add_u64 v[42:43], v[30:31], 0, v[42:43]
	v_lshl_add_u64 v[44:45], v[30:31], 0, v[44:45]
	v_lshlrev_b64 v[46:47], 12, v[46:47]
	v_lshl_add_u64 v[46:47], v[30:31], 0, v[46:47]
	global_load_dword v56, v[32:33], off
	global_load_dword v57, v[34:35], off
	global_load_dword v58, v[36:37], off
	global_load_dword v59, v[38:39], off
	global_load_dword v60, v[40:41], off
	global_load_dword v61, v[42:43], off
	global_load_dword v62, v[44:45], off
	global_load_dword v63, v[46:47], off
	v_or_b32_e32 v32, 32, v2
	v_mov_b32_e32 v33, v3
	v_or_b32_e32 v34, 34, v2
	v_mov_b32_e32 v35, v3
	v_or_b32_e32 v36, 36, v2
	v_mov_b32_e32 v37, v3
	v_or_b32_e32 v38, 38, v2
	v_mov_b32_e32 v39, v3
	v_or_b32_e32 v40, 40, v2
	v_mov_b32_e32 v41, v3
	v_or_b32_e32 v42, 42, v2
	v_mov_b32_e32 v43, v3
	v_or_b32_e32 v44, 44, v2
	v_mov_b32_e32 v45, v3
	v_lshlrev_b64 v[32:33], 12, v[32:33]
	v_lshlrev_b64 v[34:35], 12, v[34:35]
	v_lshlrev_b64 v[36:37], 12, v[36:37]
	v_lshlrev_b64 v[38:39], 12, v[38:39]
	v_lshlrev_b64 v[40:41], 12, v[40:41]
	v_lshlrev_b64 v[42:43], 12, v[42:43]
	v_lshlrev_b64 v[44:45], 12, v[44:45]
	v_or_b32_e32 v46, 46, v2
	v_mov_b32_e32 v47, v3
	v_lshl_add_u64 v[32:33], v[30:31], 0, v[32:33]
	v_lshl_add_u64 v[34:35], v[30:31], 0, v[34:35]
	v_lshl_add_u64 v[36:37], v[30:31], 0, v[36:37]
	v_lshl_add_u64 v[38:39], v[30:31], 0, v[38:39]
	v_lshl_add_u64 v[40:41], v[30:31], 0, v[40:41]
	v_lshl_add_u64 v[42:43], v[30:31], 0, v[42:43]
	v_lshl_add_u64 v[44:45], v[30:31], 0, v[44:45]
	v_lshlrev_b64 v[46:47], 12, v[46:47]
	v_lshl_add_u64 v[46:47], v[30:31], 0, v[46:47]
	global_load_dword v64, v[32:33], off
	global_load_dword v65, v[34:35], off
	global_load_dword v66, v[36:37], off
	global_load_dword v67, v[38:39], off
	global_load_dword v68, v[40:41], off
	global_load_dword v69, v[42:43], off
	global_load_dword v70, v[44:45], off
	global_load_dword v71, v[46:47], off
	v_or_b32_e32 v32, 48, v2
	v_mov_b32_e32 v33, v3
	v_or_b32_e32 v34, 50, v2
	v_mov_b32_e32 v35, v3
	v_or_b32_e32 v36, 52, v2
	v_mov_b32_e32 v37, v3
	v_or_b32_e32 v38, 54, v2
	v_mov_b32_e32 v39, v3
	v_or_b32_e32 v40, 56, v2
	v_mov_b32_e32 v41, v3
	v_or_b32_e32 v42, 58, v2
	v_mov_b32_e32 v43, v3
	v_or_b32_e32 v44, 60, v2
	v_mov_b32_e32 v45, v3
	v_or_b32_e32 v2, 62, v2
	v_lshlrev_b64 v[32:33], 12, v[32:33]
	v_lshlrev_b64 v[34:35], 12, v[34:35]
	v_lshlrev_b64 v[36:37], 12, v[36:37]
	v_lshlrev_b64 v[38:39], 12, v[38:39]
	v_lshlrev_b64 v[40:41], 12, v[40:41]
	v_lshlrev_b64 v[42:43], 12, v[42:43]
	v_lshlrev_b64 v[44:45], 12, v[44:45]
	v_lshlrev_b64 v[46:47], 12, v[2:3]
	v_lshl_add_u64 v[32:33], v[30:31], 0, v[32:33]
	v_lshl_add_u64 v[34:35], v[30:31], 0, v[34:35]
	v_lshl_add_u64 v[36:37], v[30:31], 0, v[36:37]
	v_lshl_add_u64 v[38:39], v[30:31], 0, v[38:39]
	v_lshl_add_u64 v[40:41], v[30:31], 0, v[40:41]
	v_lshl_add_u64 v[42:43], v[30:31], 0, v[42:43]
	v_lshl_add_u64 v[44:45], v[30:31], 0, v[44:45]
	v_lshl_add_u64 v[30:31], v[30:31], 0, v[46:47]
	global_load_dword v2, v[32:33], off
	s_nop 0
	global_load_dword v32, v[34:35], off
	global_load_dword v33, v[36:37], off
	s_nop 0
	global_load_dword v34, v[38:39], off
	global_load_dword v35, v[40:41], off
	global_load_dword v36, v[42:43], off
	global_load_dword v37, v[44:45], off
	s_nop 0
	global_load_dword v30, v[30:31], off
	s_waitcnt vmcnt(30)
	ds_write2_b32 v17, v48, v49 offset1:66
	s_waitcnt vmcnt(28)
	ds_write2_b32 v17, v50, v51 offset0:132 offset1:198
	s_waitcnt vmcnt(26)
	ds_write2_b32 v23, v52, v53 offset0:8 offset1:74
	s_waitcnt vmcnt(24)
	ds_write2_b32 v23, v54, v55 offset0:140 offset1:206
	s_waitcnt vmcnt(22)
	ds_write2_b32 v24, v56, v57 offset0:16 offset1:82
	s_waitcnt vmcnt(20)
	ds_write2_b32 v24, v58, v59 offset0:148 offset1:214
	s_waitcnt vmcnt(18)
	ds_write2_b32 v25, v60, v61 offset0:24 offset1:90
	s_waitcnt vmcnt(16)
	ds_write2_b32 v25, v62, v63 offset0:156 offset1:222
	s_waitcnt vmcnt(14)
	ds_write2_b32 v26, v64, v65 offset0:32 offset1:98
	s_waitcnt vmcnt(12)
	ds_write2_b32 v26, v66, v67 offset0:164 offset1:230
	s_waitcnt vmcnt(10)
	ds_write2_b32 v27, v68, v69 offset0:40 offset1:106
	s_waitcnt vmcnt(8)
	ds_write2_b32 v27, v70, v71 offset0:172 offset1:238
	s_waitcnt vmcnt(6)
	ds_write2_b32 v28, v2, v32 offset0:48 offset1:114
	s_waitcnt vmcnt(4)
	ds_write2_b32 v28, v33, v34 offset0:180 offset1:246
	s_waitcnt vmcnt(2)
	ds_write2_b32 v29, v35, v36 offset0:56 offset1:122
	s_waitcnt vmcnt(0)
	ds_write2_b32 v29, v37, v30 offset0:188 offset1:254
	s_waitcnt lgkmcnt(0)
	ds_read2_b32 v[34:35], v19 offset1:8
	ds_read2_b32 v[38:39], v19 offset0:33 offset1:41
	ds_read2_b32 v[40:41], v19 offset0:66 offset1:74
	ds_read2_b32 v[42:43], v19 offset0:99 offset1:107
	ds_read2_b32 v[44:45], v19 offset0:132 offset1:140
	s_waitcnt lgkmcnt(4)
	s_waitcnt lgkmcnt(3)
	ds_read2_b32 v[46:47], v19 offset0:165 offset1:173
	v_cvt_pk_bf16_f32 v30, v34, v38
	s_waitcnt lgkmcnt(3)
	s_waitcnt lgkmcnt(2)
	ds_read2_b32 v[48:49], v19 offset0:198 offset1:206
	ds_read2_b32 v[50:51], v19 offset0:231 offset1:239
	v_cvt_pk_bf16_f32 v31, v40, v42
	s_waitcnt lgkmcnt(3)
	s_waitcnt lgkmcnt(2)
	v_cvt_pk_bf16_f32 v32, v44, v46
	s_waitcnt lgkmcnt(1)
	s_waitcnt lgkmcnt(0)
	s_lshl_b32 s0, s5, 1
	v_cvt_pk_bf16_f32 v33, v48, v50
	v_or_b32_e32 v2, s4, v18
	v_lshl_add_u64 v[36:37], v[6:7], 0, s[0:1]
	v_mul_u32_u24_e32 v2, 0x1600, v2
	v_lshl_add_u64 v[52:53], v[36:37], 0, v[2:3]
	global_store_dwordx4 v[52:53], v[30:33], off
	s_nop 1
	v_cvt_pk_bf16_f32 v30, v35, v39
	v_cvt_pk_bf16_f32 v31, v41, v43
	v_cvt_pk_bf16_f32 v32, v45, v47
	v_cvt_pk_bf16_f32 v33, v49, v51
	v_or_b32_e32 v2, s4, v20
	v_mul_u32_u24_e32 v2, 0x1600, v2
	ds_read2_b32 v[34:35], v19 offset0:16 offset1:24
	v_lshl_add_u64 v[38:39], v[36:37], 0, v[2:3]
	global_store_dwordx4 v[38:39], v[30:33], off
	s_nop 1
	ds_read2_b32 v[38:39], v19 offset0:49 offset1:57
	ds_read2_b32 v[40:41], v19 offset0:82 offset1:90
	ds_read2_b32 v[42:43], v19 offset0:115 offset1:123
	s_waitcnt lgkmcnt(3)
	s_waitcnt lgkmcnt(2)
	ds_read2_b32 v[44:45], v19 offset0:148 offset1:156
	ds_read2_b32 v[46:47], v19 offset0:181 offset1:189
	v_cvt_pk_bf16_f32 v30, v34, v38
	s_waitcnt lgkmcnt(3)
	s_waitcnt lgkmcnt(2)
	ds_read2_b32 v[48:49], v19 offset0:214 offset1:222
	ds_read2_b32 v[50:51], v19 offset0:247 offset1:255
	v_cvt_pk_bf16_f32 v31, v40, v42
	s_waitcnt lgkmcnt(3)
	s_waitcnt lgkmcnt(2)
	v_cvt_pk_bf16_f32 v32, v44, v46
	s_waitcnt lgkmcnt(1)
	s_waitcnt lgkmcnt(0)
	v_cvt_pk_bf16_f32 v33, v48, v50
	v_or_b32_e32 v2, s4, v21
	v_mul_u32_u24_e32 v2, 0x1600, v2
	v_lshl_add_u64 v[52:53], v[36:37], 0, v[2:3]
	global_store_dwordx4 v[52:53], v[30:33], off
	s_nop 1
	v_cvt_pk_bf16_f32 v30, v35, v39
	v_cvt_pk_bf16_f32 v31, v41, v43
	v_cvt_pk_bf16_f32 v32, v45, v47
	v_cvt_pk_bf16_f32 v33, v49, v51
	v_or_b32_e32 v2, s4, v22
	v_mul_u32_u24_e32 v2, 0x1600, v2
	v_lshl_add_u64 v[34:35], v[36:37], 0, v[2:3]
	global_store_dwordx4 v[34:35], v[30:33], off
	s_nop 1
	s_waitcnt lgkmcnt(0)
	s_mov_b64 s[4:5], 0

.LBB0_97:
	s_lshl_b32 s0, s0, 6
	s_and_b32 s4, s0, 0x7fc0
	v_or_b32_e32 v2, s4, v16
	s_lshl_b32 s0, s7, 2
	v_lshl_add_u64 v[30:31], v[8:9], 0, s[0:1]
	v_mul_u32_u24_e32 v2, 0x5800, v2
	v_lshl_add_u64 v[30:31], v[30:31], 0, v[2:3]
	v_add_co_u32_e32 v32, vcc, 0xb000, v30
	s_lshl_b32 s0, s4, 1
	s_nop 0
	v_addc_co_u32_e32 v33, vcc, 0, v31, vcc
	v_add_co_u32_e32 v34, vcc, 0x16000, v30
	s_nop 1
	v_addc_co_u32_e32 v35, vcc, 0, v31, vcc
	v_add_co_u32_e32 v36, vcc, 0x21000, v30
	s_nop 1
	v_addc_co_u32_e32 v37, vcc, 0, v31, vcc
	v_add_co_u32_e32 v38, vcc, 0x2c000, v30
	s_nop 1
	v_addc_co_u32_e32 v39, vcc, 0, v31, vcc
	v_add_co_u32_e32 v40, vcc, 0x37000, v30
	s_nop 1
	v_addc_co_u32_e32 v41, vcc, 0, v31, vcc
	v_add_co_u32_e32 v42, vcc, 0x42000, v30
	s_nop 1
	v_addc_co_u32_e32 v43, vcc, 0, v31, vcc
	v_add_co_u32_e32 v44, vcc, 0x4d000, v30
	s_nop 1
	v_addc_co_u32_e32 v45, vcc, 0, v31, vcc
	global_load_dword v2, v[30:31], off
	global_load_dword v48, v[32:33], off
	global_load_dword v49, v[34:35], off
	global_load_dword v50, v[36:37], off
	global_load_dword v51, v[38:39], off
	global_load_dword v52, v[40:41], off
	global_load_dword v53, v[42:43], off
	global_load_dword v54, v[44:45], off
	v_add_co_u32_e32 v32, vcc, 0x58000, v30
	s_nop 1
	v_addc_co_u32_e32 v33, vcc, 0, v31, vcc
	v_add_co_u32_e32 v34, vcc, 0x63000, v30
	s_nop 1
	v_addc_co_u32_e32 v35, vcc, 0, v31, vcc
	v_add_co_u32_e32 v36, vcc, 0x6e000, v30
	s_nop 1
	v_addc_co_u32_e32 v37, vcc, 0, v31, vcc
	v_add_co_u32_e32 v38, vcc, 0x79000, v30
	s_nop 1
	v_addc_co_u32_e32 v39, vcc, 0, v31, vcc
	v_add_co_u32_e32 v40, vcc, 0x84000, v30
	s_nop 1
	v_addc_co_u32_e32 v41, vcc, 0, v31, vcc
	v_add_co_u32_e32 v42, vcc, 0x8f000, v30
	s_nop 1
	v_addc_co_u32_e32 v43, vcc, 0, v31, vcc
	v_add_co_u32_e32 v44, vcc, 0x9a000, v30
	s_nop 1
	v_addc_co_u32_e32 v45, vcc, 0, v31, vcc
	v_add_co_u32_e32 v46, vcc, 0xa5000, v30
	s_nop 1
	v_addc_co_u32_e32 v47, vcc, 0, v31, vcc
	global_load_dword v55, v[32:33], off
	global_load_dword v56, v[34:35], off
	global_load_dword v57, v[36:37], off
	global_load_dword v58, v[38:39], off
	global_load_dword v59, v[40:41], off
	global_load_dword v60, v[42:43], off
	global_load_dword v61, v[44:45], off
	global_load_dword v62, v[46:47], off
	v_add_co_u32_e32 v32, vcc, 0xb0000, v30
	s_nop 1
	v_addc_co_u32_e32 v33, vcc, 0, v31, vcc
	v_add_co_u32_e32 v34, vcc, 0xbb000, v30
	s_nop 1
	v_addc_co_u32_e32 v35, vcc, 0, v31, vcc
	v_add_co_u32_e32 v36, vcc, 0xc6000, v30
	s_nop 1
	v_addc_co_u32_e32 v37, vcc, 0, v31, vcc
	v_add_co_u32_e32 v38, vcc, 0xd1000, v30
	s_nop 1
	v_addc_co_u32_e32 v39, vcc, 0, v31, vcc
	v_add_co_u32_e32 v40, vcc, 0xdc000, v30
	s_nop 1
	v_addc_co_u32_e32 v41, vcc, 0, v31, vcc
	v_add_co_u32_e32 v42, vcc, 0xe7000, v30
	s_nop 1
	v_addc_co_u32_e32 v43, vcc, 0, v31, vcc
	v_add_co_u32_e32 v44, vcc, 0xf2000, v30
	s_nop 1
	v_addc_co_u32_e32 v45, vcc, 0, v31, vcc
	v_add_co_u32_e32 v46, vcc, 0xfd000, v30
	s_nop 1
	v_addc_co_u32_e32 v47, vcc, 0, v31, vcc
	global_load_dword v63, v[32:33], off
	global_load_dword v64, v[34:35], off
	global_load_dword v65, v[36:37], off
	global_load_dword v66, v[38:39], off
	global_load_dword v67, v[40:41], off
	global_load_dword v68, v[42:43], off
	global_load_dword v69, v[44:45], off
	s_nop 0
	global_load_dword v46, v[46:47], off
	v_add_co_u32_e32 v32, vcc, 0x108000, v30
	s_nop 1
	v_addc_co_u32_e32 v33, vcc, 0, v31, vcc
	v_add_co_u32_e32 v34, vcc, 0x113000, v30
	s_nop 1
	v_addc_co_u32_e32 v35, vcc, 0, v31, vcc
	v_add_co_u32_e32 v36, vcc, 0x11e000, v30
	s_nop 1
	v_addc_co_u32_e32 v37, vcc, 0, v31, vcc
	v_add_co_u32_e32 v38, vcc, 0x129000, v30
	s_nop 1
	v_addc_co_u32_e32 v39, vcc, 0, v31, vcc
	v_add_co_u32_e32 v40, vcc, 0x134000, v30
	s_nop 1
	v_addc_co_u32_e32 v41, vcc, 0, v31, vcc
	v_add_co_u32_e32 v42, vcc, 0x13f000, v30
	s_nop 1
	v_addc_co_u32_e32 v43, vcc, 0, v31, vcc
	v_add_co_u32_e32 v44, vcc, 0x14a000, v30
	s_nop 1
	v_addc_co_u32_e32 v45, vcc, 0, v31, vcc
	v_add_co_u32_e32 v30, vcc, 0x155000, v30
	s_nop 1
	v_addc_co_u32_e32 v31, vcc, 0, v31, vcc
	global_load_dword v32, v[32:33], off
	s_nop 0
	global_load_dword v33, v[34:35], off
	s_nop 0
	global_load_dword v34, v[36:37], off
	global_load_dword v35, v[38:39], off
	s_nop 0
	global_load_dword v36, v[40:41], off
	global_load_dword v37, v[42:43], off
	global_load_dword v38, v[44:45], off
	s_nop 0
	global_load_dword v30, v[30:31], off
	s_waitcnt vmcnt(30)
	ds_write2_b32 v17, v2, v48 offset1:66
	s_waitcnt vmcnt(28)
	ds_write2_b32 v17, v49, v50 offset0:132 offset1:198
	s_waitcnt vmcnt(26)
	ds_write2_b32 v23, v51, v52 offset0:8 offset1:74
	s_waitcnt vmcnt(24)
	ds_write2_b32 v23, v53, v54 offset0:140 offset1:206
	s_waitcnt vmcnt(22)
	ds_write2_b32 v24, v55, v56 offset0:16 offset1:82
	s_waitcnt vmcnt(20)
	ds_write2_b32 v24, v57, v58 offset0:148 offset1:214
	s_waitcnt vmcnt(18)
	ds_write2_b32 v25, v59, v60 offset0:24 offset1:90
	s_waitcnt vmcnt(16)
	ds_write2_b32 v25, v61, v62 offset0:156 offset1:222
	s_waitcnt vmcnt(14)
	ds_write2_b32 v26, v63, v64 offset0:32 offset1:98
	s_waitcnt vmcnt(12)
	ds_write2_b32 v26, v65, v66 offset0:164 offset1:230
	s_waitcnt vmcnt(10)
	ds_write2_b32 v27, v67, v68 offset0:40 offset1:106
	s_waitcnt vmcnt(8)
	ds_write2_b32 v27, v69, v46 offset0:172 offset1:238
	s_waitcnt vmcnt(6)
	ds_write2_b32 v28, v32, v33 offset0:48 offset1:114
	s_waitcnt vmcnt(4)
	ds_write2_b32 v28, v34, v35 offset0:180 offset1:246
	s_waitcnt vmcnt(2)
	ds_write2_b32 v29, v36, v37 offset0:56 offset1:122
	s_waitcnt vmcnt(0)
	ds_write2_b32 v29, v38, v30 offset0:188 offset1:254
	s_waitcnt lgkmcnt(0)
	ds_read2_b32 v[34:35], v19 offset1:8
	ds_read2_b32 v[38:39], v19 offset0:33 offset1:41
	ds_read2_b32 v[40:41], v19 offset0:66 offset1:74
	ds_read2_b32 v[42:43], v19 offset0:99 offset1:107
	ds_read2_b32 v[44:45], v19 offset0:132 offset1:140
	s_waitcnt lgkmcnt(4)
	s_waitcnt lgkmcnt(3)
	ds_read2_b32 v[46:47], v19 offset0:165 offset1:173
	v_cvt_pk_bf16_f32 v30, v34, v38
	s_waitcnt lgkmcnt(3)
	s_waitcnt lgkmcnt(2)
	ds_read2_b32 v[48:49], v19 offset0:198 offset1:206
	ds_read2_b32 v[50:51], v19 offset0:231 offset1:239
	v_cvt_pk_bf16_f32 v31, v40, v42
	s_waitcnt lgkmcnt(3)
	s_waitcnt lgkmcnt(2)
	v_cvt_pk_bf16_f32 v32, v44, v46
	s_waitcnt lgkmcnt(1)
	s_waitcnt lgkmcnt(0)
	v_cvt_pk_bf16_f32 v33, v48, v50
	v_add_u32_e32 v2, s6, v18
	v_lshl_add_u64 v[36:37], v[10:11], 0, s[0:1]
	v_lshlrev_b64 v[52:53], 11, v[2:3]
	v_lshl_add_u64 v[52:53], v[36:37], 0, v[52:53]
	global_store_dwordx4 v[52:53], v[30:33], off
	s_nop 1
	v_cvt_pk_bf16_f32 v30, v35, v39
	v_cvt_pk_bf16_f32 v31, v41, v43
	v_cvt_pk_bf16_f32 v32, v45, v47
	v_cvt_pk_bf16_f32 v33, v49, v51
	v_add_u32_e32 v2, s6, v20
	v_lshlrev_b64 v[38:39], 11, v[2:3]
	ds_read2_b32 v[34:35], v19 offset0:16 offset1:24
	v_lshl_add_u64 v[38:39], v[36:37], 0, v[38:39]
	global_store_dwordx4 v[38:39], v[30:33], off
	s_nop 1
	ds_read2_b32 v[38:39], v19 offset0:49 offset1:57
	ds_read2_b32 v[40:41], v19 offset0:82 offset1:90
	ds_read2_b32 v[42:43], v19 offset0:115 offset1:123
	s_waitcnt lgkmcnt(3)
	s_waitcnt lgkmcnt(2)
	ds_read2_b32 v[44:45], v19 offset0:148 offset1:156
	ds_read2_b32 v[46:47], v19 offset0:181 offset1:189
	v_cvt_pk_bf16_f32 v30, v34, v38
	s_waitcnt lgkmcnt(3)
	s_waitcnt lgkmcnt(2)
	ds_read2_b32 v[48:49], v19 offset0:214 offset1:222
	ds_read2_b32 v[50:51], v19 offset0:247 offset1:255
	v_cvt_pk_bf16_f32 v31, v40, v42
	s_waitcnt lgkmcnt(3)
	s_waitcnt lgkmcnt(2)
	v_cvt_pk_bf16_f32 v32, v44, v46
	s_waitcnt lgkmcnt(1)
	s_waitcnt lgkmcnt(0)
	v_cvt_pk_bf16_f32 v33, v48, v50
	v_add_u32_e32 v2, s6, v21
	v_lshlrev_b64 v[52:53], 11, v[2:3]
	v_lshl_add_u64 v[52:53], v[36:37], 0, v[52:53]
	global_store_dwordx4 v[52:53], v[30:33], off
	s_nop 1
	v_cvt_pk_bf16_f32 v30, v35, v39
	v_cvt_pk_bf16_f32 v31, v41, v43
	v_cvt_pk_bf16_f32 v32, v45, v47
	v_cvt_pk_bf16_f32 v33, v49, v51
	v_add_u32_e32 v2, s6, v22
	v_lshlrev_b64 v[34:35], 11, v[2:3]
	v_lshl_add_u64 v[34:35], v[36:37], 0, v[34:35]
	global_store_dwordx4 v[34:35], v[30:33], off
	s_nop 1
	s_waitcnt lgkmcnt(0)

.LBB0_107:
	s_lshl_b32 s4, s33, 6
	s_ashr_i32 s87, s86, 31
	v_or_b32_e32 v2, s4, v48
	v_lshl_add_u64 v[28:29], s[86:87], 2, v[24:25]
	v_mad_i64_i32 v[30:31], s[68:69], v2, s13, v[28:29]
	global_load_dword v32, v[30:31], off
	v_or_b32_e32 v30, 2, v2
	v_mad_i64_i32 v[30:31], s[68:69], v30, s13, v[28:29]
	global_load_dword v33, v[30:31], off
	v_or_b32_e32 v30, 4, v2
	v_mad_i64_i32 v[30:31], s[68:69], v30, s13, v[28:29]
	global_load_dword v34, v[30:31], off
	v_or_b32_e32 v30, 6, v2
	v_mad_i64_i32 v[30:31], s[68:69], v30, s13, v[28:29]
	global_load_dword v35, v[30:31], off
	v_or_b32_e32 v30, 8, v2
	v_mad_i64_i32 v[30:31], s[68:69], v30, s13, v[28:29]
	global_load_dword v36, v[30:31], off
	v_or_b32_e32 v30, 10, v2
	v_mad_i64_i32 v[30:31], s[68:69], v30, s13, v[28:29]
	global_load_dword v37, v[30:31], off
	v_or_b32_e32 v30, 12, v2
	v_mad_i64_i32 v[30:31], s[68:69], v30, s13, v[28:29]
	global_load_dword v38, v[30:31], off
	v_or_b32_e32 v30, 14, v2
	v_mad_i64_i32 v[30:31], s[68:69], v30, s13, v[28:29]
	global_load_dword v39, v[30:31], off
	v_or_b32_e32 v30, 16, v2
	v_mad_i64_i32 v[30:31], s[68:69], v30, s13, v[28:29]
	global_load_dword v40, v[30:31], off
	v_or_b32_e32 v30, 18, v2
	v_mad_i64_i32 v[30:31], s[68:69], v30, s13, v[28:29]
	global_load_dword v41, v[30:31], off
	v_or_b32_e32 v30, 20, v2
	v_mad_i64_i32 v[30:31], s[68:69], v30, s13, v[28:29]
	global_load_dword v42, v[30:31], off
	v_or_b32_e32 v30, 22, v2
	v_mad_i64_i32 v[30:31], s[68:69], v30, s13, v[28:29]
	global_load_dword v43, v[30:31], off
	v_or_b32_e32 v30, 24, v2
	v_mad_i64_i32 v[30:31], s[68:69], v30, s13, v[28:29]
	global_load_dword v44, v[30:31], off
	v_or_b32_e32 v30, 26, v2
	v_mad_i64_i32 v[30:31], s[68:69], v30, s13, v[28:29]
	global_load_dword v45, v[30:31], off
	v_or_b32_e32 v30, 28, v2
	v_mad_i64_i32 v[30:31], s[68:69], v30, s13, v[28:29]
	global_load_dword v46, v[30:31], off
	v_or_b32_e32 v30, 30, v2
	v_mad_i64_i32 v[30:31], s[68:69], v30, s13, v[28:29]
	global_load_dword v47, v[30:31], off
	v_or_b32_e32 v30, 32, v2
	v_mad_i64_i32 v[30:31], s[68:69], v30, s13, v[28:29]
	global_load_dword v60, v[30:31], off
	v_or_b32_e32 v30, 34, v2
	v_mad_i64_i32 v[30:31], s[68:69], v30, s13, v[28:29]
	global_load_dword v61, v[30:31], off
	v_or_b32_e32 v30, 36, v2
	v_mad_i64_i32 v[30:31], s[68:69], v30, s13, v[28:29]
	global_load_dword v62, v[30:31], off
	v_or_b32_e32 v30, 38, v2
	v_mad_i64_i32 v[30:31], s[68:69], v30, s13, v[28:29]
	global_load_dword v63, v[30:31], off
	v_or_b32_e32 v30, 40, v2
	v_mad_i64_i32 v[30:31], s[68:69], v30, s13, v[28:29]
	global_load_dword v64, v[30:31], off
	v_or_b32_e32 v30, 42, v2
	v_mad_i64_i32 v[30:31], s[68:69], v30, s13, v[28:29]
	global_load_dword v65, v[30:31], off
	v_or_b32_e32 v30, 44, v2
	v_mad_i64_i32 v[30:31], s[68:69], v30, s13, v[28:29]
	global_load_dword v66, v[30:31], off
	v_or_b32_e32 v30, 46, v2
	v_mad_i64_i32 v[30:31], s[68:69], v30, s13, v[28:29]
	global_load_dword v67, v[30:31], off
	v_or_b32_e32 v30, 48, v2
	v_mad_i64_i32 v[30:31], s[68:69], v30, s13, v[28:29]
	global_load_dword v68, v[30:31], off
	v_or_b32_e32 v30, 50, v2
	v_mad_i64_i32 v[30:31], s[68:69], v30, s13, v[28:29]
	global_load_dword v69, v[30:31], off
	v_or_b32_e32 v30, 52, v2
	v_mad_i64_i32 v[30:31], s[68:69], v30, s13, v[28:29]
	global_load_dword v70, v[30:31], off
	v_or_b32_e32 v30, 54, v2
	v_mad_i64_i32 v[30:31], s[68:69], v30, s13, v[28:29]
	global_load_dword v71, v[30:31], off
	v_or_b32_e32 v30, 56, v2
	v_mad_i64_i32 v[30:31], s[68:69], v30, s13, v[28:29]
	global_load_dword v72, v[30:31], off
	v_or_b32_e32 v30, 58, v2
	v_mad_i64_i32 v[30:31], s[68:69], v30, s13, v[28:29]
	global_load_dword v73, v[30:31], off
	v_or_b32_e32 v30, 60, v2
	v_or_b32_e32 v2, 62, v2
	v_mad_i64_i32 v[30:31], s[68:69], v30, s13, v[28:29]
	v_mad_i64_i32 v[28:29], s[68:69], v2, s13, v[28:29]
	global_load_dword v30, v[30:31], off
	s_ashr_i32 s5, s4, 31
	global_load_dword v2, v[28:29], off
	v_add_u32_e32 v28, 0x400, v49
	s_waitcnt vmcnt(30)
	ds_write2_b32 v49, v32, v33 offset1:66
	s_waitcnt vmcnt(28)
	ds_write2_b32 v49, v34, v35 offset0:132 offset1:198
	s_waitcnt vmcnt(26)
	ds_write2_b32 v28, v36, v37 offset0:8 offset1:74
	s_waitcnt vmcnt(24)
	ds_write2_b32 v28, v38, v39 offset0:140 offset1:206
	v_add_u32_e32 v28, 0x800, v49
	s_waitcnt vmcnt(22)
	ds_write2_b32 v28, v40, v41 offset0:16 offset1:82
	s_waitcnt vmcnt(20)
	ds_write2_b32 v28, v42, v43 offset0:148 offset1:214
	v_add_u32_e32 v28, 0xc00, v49
	s_waitcnt vmcnt(18)
	ds_write2_b32 v28, v44, v45 offset0:24 offset1:90
	s_waitcnt vmcnt(16)
	ds_write2_b32 v28, v46, v47 offset0:156 offset1:222
	v_add_u32_e32 v28, 0x1000, v49
	s_waitcnt vmcnt(14)
	ds_write2_b32 v28, v60, v61 offset0:32 offset1:98
	s_waitcnt vmcnt(12)
	ds_write2_b32 v28, v62, v63 offset0:164 offset1:230
	v_add_u32_e32 v28, 0x1400, v49
	s_waitcnt vmcnt(10)
	ds_write2_b32 v28, v64, v65 offset0:40 offset1:106
	s_waitcnt vmcnt(8)
	ds_write2_b32 v28, v66, v67 offset0:172 offset1:238
	v_add_u32_e32 v28, 0x1800, v49
	s_waitcnt vmcnt(6)
	ds_write2_b32 v28, v68, v69 offset0:48 offset1:114
	s_waitcnt vmcnt(4)
	ds_write2_b32 v28, v70, v71 offset0:180 offset1:246
	v_add_u32_e32 v28, 0x1c00, v49
	s_waitcnt vmcnt(2)
	ds_write2_b32 v28, v72, v73 offset0:56 offset1:122
	s_waitcnt vmcnt(0)
	ds_write2_b32 v28, v30, v2 offset0:188 offset1:254
	s_waitcnt lgkmcnt(0)
	ds_read2_b32 v[34:35], v1 offset0:33 offset1:41
	ds_read2_b32 v[36:37], v1 offset1:8
	ds_read2_b32 v[38:39], v1 offset0:66 offset1:74
	ds_read2_b32 v[40:41], v1 offset0:99 offset1:107
	ds_read2_b32 v[42:43], v1 offset0:132 offset1:140
	ds_read2_b32 v[44:45], v1 offset0:165 offset1:173
	ds_read2_b32 v[46:47], v1 offset0:198 offset1:206
	ds_read2_b32 v[60:61], v1 offset0:231 offset1:239
	s_waitcnt lgkmcnt(7)
	s_waitcnt lgkmcnt(6)
	v_cvt_pk_bf16_f32 v30, v36, v34
	s_waitcnt lgkmcnt(5)
	s_waitcnt lgkmcnt(4)
	v_cvt_pk_bf16_f32 v31, v38, v40
	s_waitcnt lgkmcnt(3)
	s_waitcnt lgkmcnt(2)
	v_cvt_pk_bf16_f32 v32, v42, v44
	s_waitcnt lgkmcnt(1)
	v_add_u32_e32 v62, s6, v50
	s_waitcnt lgkmcnt(0)
	v_ashrrev_i32_e32 v63, 31, v62
	v_lshl_add_u64 v[28:29], s[4:5], 1, v[26:27]
	v_lshlrev_b64 v[62:63], 11, v[62:63]
	v_cvt_pk_bf16_f32 v33, v46, v60
	v_lshl_add_u64 v[62:63], v[28:29], 0, v[62:63]
	global_store_dwordx4 v[62:63], v[30:33], off
	s_nop 1
	v_cvt_pk_bf16_f32 v30, v37, v35
	v_cvt_pk_bf16_f32 v31, v39, v41
	v_cvt_pk_bf16_f32 v32, v43, v45
	v_add_u32_e32 v34, s6, v51
	v_ashrrev_i32_e32 v35, 31, v34
	v_lshlrev_b64 v[34:35], 11, v[34:35]
	v_cvt_pk_bf16_f32 v33, v47, v61
	v_lshl_add_u64 v[34:35], v[28:29], 0, v[34:35]
	global_store_dwordx4 v[34:35], v[30:33], off
	s_nop 1
	ds_read2_b32 v[34:35], v1 offset0:49 offset1:57
	ds_read2_b32 v[36:37], v1 offset0:16 offset1:24
	ds_read2_b32 v[38:39], v1 offset0:82 offset1:90
	ds_read2_b32 v[40:41], v1 offset0:115 offset1:123
	ds_read2_b32 v[42:43], v1 offset0:148 offset1:156
	ds_read2_b32 v[44:45], v1 offset0:181 offset1:189
	ds_read2_b32 v[46:47], v1 offset0:214 offset1:222
	ds_read2_b32 v[60:61], v1 offset0:247 offset1:255
	s_waitcnt lgkmcnt(7)
	s_waitcnt lgkmcnt(6)
	v_cvt_pk_bf16_f32 v30, v36, v34
	s_waitcnt lgkmcnt(5)
	s_waitcnt lgkmcnt(4)
	v_cvt_pk_bf16_f32 v31, v38, v40
	s_waitcnt lgkmcnt(3)
	s_waitcnt lgkmcnt(2)
	v_cvt_pk_bf16_f32 v32, v42, v44
	s_waitcnt lgkmcnt(1)
	v_add_u32_e32 v62, s6, v52
	s_waitcnt lgkmcnt(0)
	v_ashrrev_i32_e32 v63, 31, v62
	v_lshlrev_b64 v[62:63], 11, v[62:63]
	v_cvt_pk_bf16_f32 v33, v46, v60
	v_lshl_add_u64 v[62:63], v[28:29], 0, v[62:63]
	global_store_dwordx4 v[62:63], v[30:33], off
	s_nop 1
	v_cvt_pk_bf16_f32 v30, v37, v35
	v_cvt_pk_bf16_f32 v31, v39, v41
	v_cvt_pk_bf16_f32 v32, v43, v45
	v_add_u32_e32 v34, s6, v53
	v_ashrrev_i32_e32 v35, 31, v34
	v_lshlrev_b64 v[34:35], 11, v[34:35]
	v_cvt_pk_bf16_f32 v33, v47, v61
	v_lshl_add_u64 v[28:29], v[28:29], 0, v[34:35]
	global_store_dwordx4 v[28:29], v[30:33], off
	s_nop 1
	s_waitcnt lgkmcnt(0)

.LBB0_138:
	s_waitcnt vmcnt(4)
	ds_write2_b32 v2, v30, v31 offset0:172 offset1:238
	s_waitcnt lgkmcnt(0)
	ds_read2_b32 v[32:33], v1 offset1:8
	ds_read2_b32 v[34:35], v1 offset0:33 offset1:41
	ds_read2_b32 v[38:39], v1 offset0:66 offset1:74
	ds_read2_b32 v[40:41], v1 offset0:99 offset1:107
	ds_read2_b32 v[42:43], v1 offset0:132 offset1:140
	s_waitcnt lgkmcnt(4)
	s_waitcnt vmcnt(1) lgkmcnt(3)
	ds_read2_b32 v[44:45], v1 offset0:165 offset1:173
	v_cvt_pk_bf16_f32 v28, v32, v34
	s_waitcnt lgkmcnt(3)
	s_waitcnt vmcnt(0) lgkmcnt(2)
	ds_read2_b32 v[46:47], v1 offset0:198 offset1:206
	ds_read2_b32 v[60:61], v1 offset0:231 offset1:239
	v_cvt_pk_bf16_f32 v29, v38, v40
	s_waitcnt lgkmcnt(3)
	s_waitcnt lgkmcnt(2)
	v_cvt_pk_bf16_f32 v30, v42, v44
	s_waitcnt lgkmcnt(1)
	s_waitcnt lgkmcnt(0)
	v_cvt_pk_bf16_f32 v31, v46, v60
	v_or_b32_e32 v2, s68, v50
	v_lshl_add_u64 v[36:37], s[6:7], 1, v[6:7]
	v_lshlrev_b32_e32 v2, 11, v2
	v_lshl_add_u64 v[62:63], v[36:37], 0, v[2:3]
	global_store_dwordx4 v[62:63], v[28:31], off
	s_nop 1
	v_cvt_pk_bf16_f32 v28, v33, v35
	v_cvt_pk_bf16_f32 v29, v39, v41
	v_cvt_pk_bf16_f32 v30, v43, v45
	v_cvt_pk_bf16_f32 v31, v47, v61
	v_or_b32_e32 v2, s68, v51
	v_lshlrev_b32_e32 v2, 11, v2
	ds_read2_b32 v[32:33], v1 offset0:16 offset1:24
	v_lshl_add_u64 v[34:35], v[36:37], 0, v[2:3]
	global_store_dwordx4 v[34:35], v[28:31], off
	s_nop 1
	ds_read2_b32 v[34:35], v1 offset0:49 offset1:57
	ds_read2_b32 v[38:39], v1 offset0:82 offset1:90
	ds_read2_b32 v[40:41], v1 offset0:115 offset1:123
	s_waitcnt lgkmcnt(3)
	s_waitcnt lgkmcnt(2)
	ds_read2_b32 v[42:43], v1 offset0:148 offset1:156
	ds_read2_b32 v[44:45], v1 offset0:181 offset1:189
	v_cvt_pk_bf16_f32 v28, v32, v34
	s_waitcnt lgkmcnt(3)
	s_waitcnt lgkmcnt(2)
	ds_read2_b32 v[46:47], v1 offset0:214 offset1:222
	ds_read2_b32 v[60:61], v1 offset0:247 offset1:255
	v_cvt_pk_bf16_f32 v29, v38, v40
	s_waitcnt lgkmcnt(3)
	s_waitcnt lgkmcnt(2)
	v_cvt_pk_bf16_f32 v30, v42, v44
	s_waitcnt lgkmcnt(1)
	s_waitcnt lgkmcnt(0)
	v_cvt_pk_bf16_f32 v31, v46, v60
	v_or_b32_e32 v2, s68, v52
	v_lshlrev_b32_e32 v2, 11, v2
	v_lshl_add_u64 v[62:63], v[36:37], 0, v[2:3]
	global_store_dwordx4 v[62:63], v[28:31], off
	s_nop 1
	v_cvt_pk_bf16_f32 v28, v33, v35
	v_cvt_pk_bf16_f32 v29, v39, v41
	v_cvt_pk_bf16_f32 v30, v43, v45
	v_cvt_pk_bf16_f32 v31, v47, v61
	v_or_b32_e32 v2, s68, v53
	v_lshlrev_b32_e32 v2, 11, v2
	v_lshl_add_u64 v[32:33], v[36:37], 0, v[2:3]
	global_store_dwordx4 v[32:33], v[28:31], off
	s_nop 1
	s_waitcnt lgkmcnt(0)
	s_mov_b64 s[4:5], 0
.LBB0_139:
	s_and_b64 vcc, exec, s[4:5]
	s_cbranch_vccz .LBB0_141
	s_add_i32 s4, s88, 0xdf00
	s_bfe_u32 s5, s4, 0xc0004
	s_mulk_i32 s5, 0x2493
	s_lshr_b32 s5, s5, 16
	s_mul_i32 s6, s5, 0x70
	s_sub_i32 s4, s4, s6
	s_and_b32 s6, s4, 0xffff
	s_lshl_b32 s4, s6, 5
	s_lshl_b32 s69, s6, 6
	s_and_b32 s68, s4, 0x100
	s_and_b32 s69, s69, 0xc0
	s_or_b32 s68, s68, s69
	s_lshl_b32 s69, s6, 3
	s_and_b32 s69, s69, 32
	s_and_b32 s33, s4, 0x1e0
	s_or_b32 s68, s68, s69
	s_cmp_lt_u32 s6, 32
	s_cselect_b32 s33, s68, s33
	s_and_b32 s68, s4, 0xe00
	s_or_b32 s69, s68, 8
	s_cmp_lt_u32 s6, 48
	s_cselect_b32 s6, s68, s69
	s_or_b32 s6, s33, s6
	v_lshl_or_b32 v2, s5, 6, v48
	s_lshl_b32 s6, s6, 2
	v_lshl_add_u64 v[28:29], v[8:9], 0, s[6:7]
	v_mul_u32_u24_e32 v2, 0x3820, v2
	v_lshl_add_u64 v[28:29], v[28:29], 0, v[2:3]
	s_movk_i32 s6, 0x7000
	v_add_co_u32_e32 v30, vcc, s6, v28
	s_mov_b32 s6, 0xe000
	s_nop 0
	v_addc_co_u32_e32 v31, vcc, 0, v29, vcc
	global_load_dword v2, v[28:29], off
	global_load_dword v32, v[30:31], off offset:64
	v_add_co_u32_e32 v30, vcc, s6, v28
	s_mov_b32 s6, 0x15000
	s_nop 0
	v_addc_co_u32_e32 v31, vcc, 0, v29, vcc
	global_load_dword v33, v[30:31], off offset:128
	v_add_co_u32_e32 v30, vcc, s6, v28
	s_mov_b32 s6, 0x1c000
	s_nop 0
	v_addc_co_u32_e32 v31, vcc, 0, v29, vcc
	global_load_dword v34, v[30:31], off offset:192
	v_add_co_u32_e32 v30, vcc, s6, v28
	s_mov_b32 s6, 0x23000
	s_nop 0
	v_addc_co_u32_e32 v31, vcc, 0, v29, vcc
	global_load_dword v35, v[30:31], off offset:256
	v_add_co_u32_e32 v30, vcc, s6, v28
	s_mov_b32 s6, 0x2a000
	s_nop 0
	v_addc_co_u32_e32 v31, vcc, 0, v29, vcc
	global_load_dword v36, v[30:31], off offset:320
	v_add_co_u32_e32 v30, vcc, s6, v28
	s_mov_b32 s6, 0x31000
	s_nop 0
	v_addc_co_u32_e32 v31, vcc, 0, v29, vcc
	global_load_dword v37, v[30:31], off offset:384
	v_add_co_u32_e32 v30, vcc, s6, v28
	s_mov_b32 s6, 0x38000
	s_nop 0
	v_addc_co_u32_e32 v31, vcc, 0, v29, vcc
	global_load_dword v38, v[30:31], off offset:448
	v_add_co_u32_e32 v30, vcc, s6, v28
	s_mov_b32 s6, 0x3f000
	s_nop 0
	v_addc_co_u32_e32 v31, vcc, 0, v29, vcc
	global_load_dword v39, v[30:31], off offset:512
	v_add_co_u32_e32 v30, vcc, s6, v28
	s_mov_b32 s6, 0x46000
	s_nop 0
	v_addc_co_u32_e32 v31, vcc, 0, v29, vcc
	global_load_dword v40, v[30:31], off offset:576
	v_add_co_u32_e32 v30, vcc, s6, v28
	s_mov_b32 s6, 0x54000
	s_nop 0
	v_addc_co_u32_e32 v31, vcc, 0, v29, vcc
	global_load_dword v41, v[30:31], off offset:640
	v_add_co_u32_e32 v30, vcc, s11, v28
	s_nop 1
	v_addc_co_u32_e32 v31, vcc, 0, v29, vcc
	global_load_dword v42, v[30:31], off offset:704
	v_add_co_u32_e32 v30, vcc, s6, v28
	s_mov_b32 s6, 0x5b000
	s_nop 0
	v_addc_co_u32_e32 v31, vcc, 0, v29, vcc
	global_load_dword v43, v[30:31], off offset:768
	v_add_co_u32_e32 v30, vcc, s6, v28
	s_mov_b32 s6, 0x62000
	s_nop 0
	v_addc_co_u32_e32 v31, vcc, 0, v29, vcc
	global_load_dword v44, v[30:31], off offset:832
	v_add_co_u32_e32 v30, vcc, s6, v28
	s_mov_b32 s6, 0x69000
	s_nop 0
	v_addc_co_u32_e32 v31, vcc, 0, v29, vcc
	global_load_dword v45, v[30:31], off offset:896
	v_add_co_u32_e32 v30, vcc, s6, v28
	s_mov_b32 s6, 0x70000
	s_nop 0
	v_addc_co_u32_e32 v31, vcc, 0, v29, vcc
	global_load_dword v46, v[30:31], off offset:960
	v_add_co_u32_e32 v30, vcc, s6, v28
	s_mov_b32 s6, 0x77000
	s_nop 0
	v_addc_co_u32_e32 v31, vcc, 0, v29, vcc
	global_load_dword v47, v[30:31], off offset:1024
	v_add_co_u32_e32 v30, vcc, s6, v28
	s_mov_b32 s6, 0x7e000
	s_nop 0
	v_addc_co_u32_e32 v31, vcc, 0, v29, vcc
	global_load_dword v60, v[30:31], off offset:1088
	v_add_co_u32_e32 v30, vcc, s6, v28
	s_mov_b32 s6, 0x85000
	s_nop 0
	v_addc_co_u32_e32 v31, vcc, 0, v29, vcc
	global_load_dword v61, v[30:31], off offset:1152
	v_add_co_u32_e32 v30, vcc, s6, v28
	s_mov_b32 s6, 0x8c000
	s_nop 0
	v_addc_co_u32_e32 v31, vcc, 0, v29, vcc
	global_load_dword v62, v[30:31], off offset:1216
	v_add_co_u32_e32 v30, vcc, s6, v28
	s_mov_b32 s6, 0x93000
	s_nop 0
	v_addc_co_u32_e32 v31, vcc, 0, v29, vcc
	global_load_dword v63, v[30:31], off offset:1280
	v_add_co_u32_e32 v30, vcc, s6, v28
	s_mov_b32 s6, 0xa1000
	s_nop 0
	v_addc_co_u32_e32 v31, vcc, 0, v29, vcc
	global_load_dword v64, v[30:31], off offset:1344
	v_add_co_u32_e32 v30, vcc, s12, v28
	s_nop 1
	v_addc_co_u32_e32 v31, vcc, 0, v29, vcc
	global_load_dword v65, v[30:31], off offset:1408
	v_add_co_u32_e32 v30, vcc, s6, v28
	s_mov_b32 s6, 0xa8000
	s_nop 0
	v_addc_co_u32_e32 v31, vcc, 0, v29, vcc
	global_load_dword v66, v[30:31], off offset:1472
	v_add_co_u32_e32 v30, vcc, s6, v28
	s_mov_b32 s6, 0xaf000
	s_nop 0
	v_addc_co_u32_e32 v31, vcc, 0, v29, vcc
	global_load_dword v67, v[30:31], off offset:1536
	v_add_co_u32_e32 v30, vcc, s6, v28
	s_mov_b32 s6, 0xb6000
	s_nop 0
	v_addc_co_u32_e32 v31, vcc, 0, v29, vcc
	global_load_dword v68, v[30:31], off offset:1600
	v_add_co_u32_e32 v30, vcc, s6, v28
	s_mov_b32 s6, 0xbd000
	s_nop 0
	v_addc_co_u32_e32 v31, vcc, 0, v29, vcc
	global_load_dword v69, v[30:31], off offset:1664
	v_add_co_u32_e32 v30, vcc, s6, v28
	s_mov_b32 s6, 0xc4000
	s_nop 0
	v_addc_co_u32_e32 v31, vcc, 0, v29, vcc
	global_load_dword v70, v[30:31], off offset:1728
	v_add_co_u32_e32 v30, vcc, s6, v28
	s_mov_b32 s6, 0xcb000
	s_nop 0
	v_addc_co_u32_e32 v31, vcc, 0, v29, vcc
	global_load_dword v71, v[30:31], off offset:1792
	v_add_co_u32_e32 v30, vcc, s6, v28
	s_mov_b32 s6, 0xd2000
	s_nop 0
	v_addc_co_u32_e32 v31, vcc, 0, v29, vcc
	global_load_dword v72, v[30:31], off offset:1856
	v_add_co_u32_e32 v30, vcc, s6, v28
	s_mov_b32 s6, 0xd9000
	s_nop 0
	v_addc_co_u32_e32 v31, vcc, 0, v29, vcc
	v_add_co_u32_e32 v28, vcc, s6, v28
	global_load_dword v30, v[30:31], off offset:1920
	s_nop 0
	v_addc_co_u32_e32 v29, vcc, 0, v29, vcc
	global_load_dword v28, v[28:29], off offset:1984
	s_waitcnt vmcnt(30)
	ds_write2_b32 v49, v2, v32 offset1:66
	s_waitcnt vmcnt(28)
	ds_write2_b32 v49, v33, v34 offset0:132 offset1:198
	v_add_u32_e32 v2, 0x400, v49
	s_waitcnt vmcnt(26)
	ds_write2_b32 v2, v35, v36 offset0:8 offset1:74
	s_waitcnt vmcnt(24)
	ds_write2_b32 v2, v37, v38 offset0:140 offset1:206
	v_add_u32_e32 v2, 0x800, v49
	s_waitcnt vmcnt(22)
	ds_write2_b32 v2, v39, v40 offset0:16 offset1:82
	s_waitcnt vmcnt(20)
	ds_write2_b32 v2, v41, v42 offset0:148 offset1:214
	v_add_u32_e32 v2, 0xc00, v49
	s_waitcnt vmcnt(18)
	ds_write2_b32 v2, v43, v44 offset0:24 offset1:90
	s_waitcnt vmcnt(16)
	ds_write2_b32 v2, v45, v46 offset0:156 offset1:222
	v_add_u32_e32 v2, 0x1000, v49
	s_waitcnt vmcnt(14)
	ds_write2_b32 v2, v47, v60 offset0:32 offset1:98
	s_waitcnt vmcnt(12)
	ds_write2_b32 v2, v61, v62 offset0:164 offset1:230
	v_add_u32_e32 v2, 0x1400, v49
	s_waitcnt vmcnt(10)
	ds_write2_b32 v2, v63, v64 offset0:40 offset1:106
	s_waitcnt vmcnt(8)
	ds_write2_b32 v2, v65, v66 offset0:172 offset1:238
	v_add_u32_e32 v2, 0x1800, v49
	s_waitcnt vmcnt(6)
	ds_write2_b32 v2, v67, v68 offset0:48 offset1:114
	s_waitcnt vmcnt(4)
	ds_write2_b32 v2, v69, v70 offset0:180 offset1:246
	v_add_u32_e32 v2, 0x1c00, v49
	s_waitcnt vmcnt(2)
	ds_write2_b32 v2, v71, v72 offset0:56 offset1:122
	s_waitcnt vmcnt(0)
	ds_write2_b32 v2, v30, v28 offset0:188 offset1:254
	s_waitcnt lgkmcnt(0)
	ds_read2_b32 v[34:35], v1 offset0:33 offset1:41
	ds_read2_b32 v[36:37], v1 offset1:8
	ds_read2_b32 v[38:39], v1 offset0:66 offset1:74
	ds_read2_b32 v[40:41], v1 offset0:99 offset1:107
	ds_read2_b32 v[42:43], v1 offset0:132 offset1:140
	ds_read2_b32 v[44:45], v1 offset0:165 offset1:173
	ds_read2_b32 v[46:47], v1 offset0:198 offset1:206
	ds_read2_b32 v[60:61], v1 offset0:231 offset1:239
	s_waitcnt lgkmcnt(7)
	s_waitcnt lgkmcnt(6)
	v_cvt_pk_bf16_f32 v30, v36, v34
	s_waitcnt lgkmcnt(5)
	s_waitcnt lgkmcnt(4)
	v_cvt_pk_bf16_f32 v31, v38, v40
	s_waitcnt lgkmcnt(3)
	s_waitcnt lgkmcnt(2)
	v_cvt_pk_bf16_f32 v32, v42, v44
	s_waitcnt lgkmcnt(1)
	s_waitcnt lgkmcnt(0)
	s_lshl_b32 s6, s5, 7
	v_cvt_pk_bf16_f32 v33, v46, v60
	v_or_b32_e32 v2, s4, v50
	v_lshl_add_u64 v[28:29], v[10:11], 0, s[6:7]
	v_lshlrev_b32_e32 v2, 11, v2
	v_lshl_add_u64 v[62:63], v[28:29], 0, v[2:3]
	global_store_dwordx4 v[62:63], v[30:33], off
	s_nop 1
	v_cvt_pk_bf16_f32 v30, v37, v35
	v_cvt_pk_bf16_f32 v31, v39, v41
	v_cvt_pk_bf16_f32 v32, v43, v45
	v_cvt_pk_bf16_f32 v33, v47, v61
	v_or_b32_e32 v2, s4, v51
	v_lshlrev_b32_e32 v2, 11, v2
	v_lshl_add_u64 v[34:35], v[28:29], 0, v[2:3]
	global_store_dwordx4 v[34:35], v[30:33], off
	s_nop 1
	ds_read2_b32 v[34:35], v1 offset0:49 offset1:57
	ds_read2_b32 v[36:37], v1 offset0:16 offset1:24
	ds_read2_b32 v[38:39], v1 offset0:82 offset1:90
	ds_read2_b32 v[40:41], v1 offset0:115 offset1:123
	ds_read2_b32 v[42:43], v1 offset0:148 offset1:156
	ds_read2_b32 v[44:45], v1 offset0:181 offset1:189
	ds_read2_b32 v[46:47], v1 offset0:214 offset1:222
	ds_read2_b32 v[60:61], v1 offset0:247 offset1:255
	s_waitcnt lgkmcnt(7)
	s_waitcnt lgkmcnt(6)
	v_cvt_pk_bf16_f32 v30, v36, v34
	s_waitcnt lgkmcnt(5)
	s_waitcnt lgkmcnt(4)
	v_cvt_pk_bf16_f32 v31, v38, v40
	s_waitcnt lgkmcnt(3)
	s_waitcnt lgkmcnt(2)
	v_cvt_pk_bf16_f32 v32, v42, v44
	s_waitcnt lgkmcnt(1)
	s_waitcnt lgkmcnt(0)
	v_cvt_pk_bf16_f32 v33, v46, v60
	v_or_b32_e32 v2, s4, v52
	v_lshlrev_b32_e32 v2, 11, v2
	v_lshl_add_u64 v[62:63], v[28:29], 0, v[2:3]
	global_store_dwordx4 v[62:63], v[30:33], off
	s_nop 1
	v_cvt_pk_bf16_f32 v30, v37, v35
	v_cvt_pk_bf16_f32 v31, v39, v41
	v_cvt_pk_bf16_f32 v32, v43, v45
	v_cvt_pk_bf16_f32 v33, v47, v61
	v_or_b32_e32 v2, s4, v53
	v_lshlrev_b32_e32 v2, 11, v2
	v_lshl_add_u64 v[28:29], v[28:29], 0, v[2:3]
	global_store_dwordx4 v[28:29], v[30:33], off
	s_nop 1
	s_waitcnt lgkmcnt(0)

.LBB0_142:
	s_andn2_b64 vcc, exec, s[4:5]
	s_cbranch_vccnz .LBB0_144
	s_add_i32 s4, s95, 0x1900
	s_and_b32 s5, s4, 0x7fffffc0
	s_and_b32 s4, s3, 0x3e0
	v_or_b32_e32 v2, s5, v48
	s_lshl_b32 s6, s4, 2
	v_lshl_add_u64 v[28:29], v[12:13], 0, s[6:7]
	v_lshlrev_b64 v[30:31], 12, v[2:3]
	v_lshl_add_u64 v[30:31], v[28:29], 0, v[30:31]
	global_load_dword v32, v[30:31], off
	v_or_b32_e32 v30, 2, v2
	v_mov_b32_e32 v31, v3
	v_lshlrev_b64 v[30:31], 12, v[30:31]
	v_lshl_add_u64 v[30:31], v[28:29], 0, v[30:31]
	global_load_dword v33, v[30:31], off
	v_or_b32_e32 v30, 4, v2
	v_mov_b32_e32 v31, v3
	v_lshlrev_b64 v[30:31], 12, v[30:31]
	v_lshl_add_u64 v[30:31], v[28:29], 0, v[30:31]
	global_load_dword v34, v[30:31], off
	v_or_b32_e32 v30, 6, v2
	v_mov_b32_e32 v31, v3
	v_lshlrev_b64 v[30:31], 12, v[30:31]
	v_lshl_add_u64 v[30:31], v[28:29], 0, v[30:31]
	global_load_dword v35, v[30:31], off
	v_or_b32_e32 v30, 8, v2
	v_mov_b32_e32 v31, v3
	v_lshlrev_b64 v[30:31], 12, v[30:31]
	v_lshl_add_u64 v[30:31], v[28:29], 0, v[30:31]
	global_load_dword v36, v[30:31], off
	v_or_b32_e32 v30, 10, v2
	v_mov_b32_e32 v31, v3
	v_lshlrev_b64 v[30:31], 12, v[30:31]
	v_lshl_add_u64 v[30:31], v[28:29], 0, v[30:31]
	global_load_dword v37, v[30:31], off
	v_or_b32_e32 v30, 12, v2
	v_mov_b32_e32 v31, v3
	v_lshlrev_b64 v[30:31], 12, v[30:31]
	v_lshl_add_u64 v[30:31], v[28:29], 0, v[30:31]
	global_load_dword v38, v[30:31], off
	v_or_b32_e32 v30, 14, v2
	v_mov_b32_e32 v31, v3
	v_lshlrev_b64 v[30:31], 12, v[30:31]
	v_lshl_add_u64 v[30:31], v[28:29], 0, v[30:31]
	global_load_dword v39, v[30:31], off
	v_or_b32_e32 v30, 16, v2
	v_mov_b32_e32 v31, v3
	v_lshlrev_b64 v[30:31], 12, v[30:31]
	v_lshl_add_u64 v[30:31], v[28:29], 0, v[30:31]
	global_load_dword v40, v[30:31], off
	v_or_b32_e32 v30, 18, v2
	v_mov_b32_e32 v31, v3
	v_lshlrev_b64 v[30:31], 12, v[30:31]
	v_lshl_add_u64 v[30:31], v[28:29], 0, v[30:31]
	global_load_dword v41, v[30:31], off
	v_or_b32_e32 v30, 20, v2
	v_mov_b32_e32 v31, v3
	v_lshlrev_b64 v[30:31], 12, v[30:31]
	v_lshl_add_u64 v[30:31], v[28:29], 0, v[30:31]
	global_load_dword v42, v[30:31], off
	v_or_b32_e32 v30, 22, v2
	v_mov_b32_e32 v31, v3
	v_lshlrev_b64 v[30:31], 12, v[30:31]
	v_lshl_add_u64 v[30:31], v[28:29], 0, v[30:31]
	global_load_dword v43, v[30:31], off
	v_or_b32_e32 v30, 24, v2
	v_mov_b32_e32 v31, v3
	v_lshlrev_b64 v[30:31], 12, v[30:31]
	v_lshl_add_u64 v[30:31], v[28:29], 0, v[30:31]
	global_load_dword v44, v[30:31], off
	v_or_b32_e32 v30, 26, v2
	v_mov_b32_e32 v31, v3
	v_lshlrev_b64 v[30:31], 12, v[30:31]
	v_lshl_add_u64 v[30:31], v[28:29], 0, v[30:31]
	global_load_dword v45, v[30:31], off
	v_or_b32_e32 v30, 28, v2
	v_mov_b32_e32 v31, v3
	v_lshlrev_b64 v[30:31], 12, v[30:31]
	v_lshl_add_u64 v[30:31], v[28:29], 0, v[30:31]
	global_load_dword v46, v[30:31], off
	v_or_b32_e32 v30, 30, v2
	v_mov_b32_e32 v31, v3
	v_lshlrev_b64 v[30:31], 12, v[30:31]
	v_lshl_add_u64 v[30:31], v[28:29], 0, v[30:31]
	global_load_dword v47, v[30:31], off
	v_or_b32_e32 v30, 32, v2
	v_mov_b32_e32 v31, v3
	v_lshlrev_b64 v[30:31], 12, v[30:31]
	v_lshl_add_u64 v[30:31], v[28:29], 0, v[30:31]
	global_load_dword v60, v[30:31], off
	v_or_b32_e32 v30, 34, v2
	v_mov_b32_e32 v31, v3
	v_lshlrev_b64 v[30:31], 12, v[30:31]
	v_lshl_add_u64 v[30:31], v[28:29], 0, v[30:31]
	global_load_dword v61, v[30:31], off
	v_or_b32_e32 v30, 36, v2
	v_mov_b32_e32 v31, v3
	v_lshlrev_b64 v[30:31], 12, v[30:31]
	v_lshl_add_u64 v[30:31], v[28:29], 0, v[30:31]
	global_load_dword v62, v[30:31], off
	v_or_b32_e32 v30, 38, v2
	v_mov_b32_e32 v31, v3
	v_lshlrev_b64 v[30:31], 12, v[30:31]
	v_lshl_add_u64 v[30:31], v[28:29], 0, v[30:31]
	global_load_dword v63, v[30:31], off
	v_or_b32_e32 v30, 40, v2
	v_mov_b32_e32 v31, v3
	v_lshlrev_b64 v[30:31], 12, v[30:31]
	v_lshl_add_u64 v[30:31], v[28:29], 0, v[30:31]
	global_load_dword v64, v[30:31], off
	v_or_b32_e32 v30, 42, v2
	v_mov_b32_e32 v31, v3
	v_lshlrev_b64 v[30:31], 12, v[30:31]
	v_lshl_add_u64 v[30:31], v[28:29], 0, v[30:31]
	global_load_dword v65, v[30:31], off
	v_or_b32_e32 v30, 44, v2
	v_mov_b32_e32 v31, v3
	v_lshlrev_b64 v[30:31], 12, v[30:31]
	v_lshl_add_u64 v[30:31], v[28:29], 0, v[30:31]
	global_load_dword v66, v[30:31], off
	v_or_b32_e32 v30, 46, v2
	v_mov_b32_e32 v31, v3
	v_lshlrev_b64 v[30:31], 12, v[30:31]
	v_lshl_add_u64 v[30:31], v[28:29], 0, v[30:31]
	global_load_dword v67, v[30:31], off
	v_or_b32_e32 v30, 48, v2
	v_mov_b32_e32 v31, v3
	v_lshlrev_b64 v[30:31], 12, v[30:31]
	v_lshl_add_u64 v[30:31], v[28:29], 0, v[30:31]
	global_load_dword v68, v[30:31], off
	v_or_b32_e32 v30, 50, v2
	v_mov_b32_e32 v31, v3
	v_lshlrev_b64 v[30:31], 12, v[30:31]
	v_lshl_add_u64 v[30:31], v[28:29], 0, v[30:31]
	global_load_dword v69, v[30:31], off
	v_or_b32_e32 v30, 52, v2
	v_mov_b32_e32 v31, v3
	v_lshlrev_b64 v[30:31], 12, v[30:31]
	v_lshl_add_u64 v[30:31], v[28:29], 0, v[30:31]
	global_load_dword v70, v[30:31], off
	v_or_b32_e32 v30, 54, v2
	v_mov_b32_e32 v31, v3
	v_lshlrev_b64 v[30:31], 12, v[30:31]
	v_lshl_add_u64 v[30:31], v[28:29], 0, v[30:31]
	global_load_dword v71, v[30:31], off
	v_or_b32_e32 v30, 56, v2
	v_mov_b32_e32 v31, v3
	v_lshlrev_b64 v[30:31], 12, v[30:31]
	v_lshl_add_u64 v[30:31], v[28:29], 0, v[30:31]
	global_load_dword v72, v[30:31], off
	v_or_b32_e32 v30, 58, v2
	v_mov_b32_e32 v31, v3
	v_lshlrev_b64 v[30:31], 12, v[30:31]
	v_lshl_add_u64 v[30:31], v[28:29], 0, v[30:31]
	global_load_dword v73, v[30:31], off
	v_or_b32_e32 v30, 60, v2
	v_mov_b32_e32 v31, v3
	v_lshlrev_b64 v[30:31], 12, v[30:31]
	v_lshl_add_u64 v[30:31], v[28:29], 0, v[30:31]
	v_or_b32_e32 v2, 62, v2
	global_load_dword v74, v[30:31], off
	v_lshlrev_b64 v[30:31], 12, v[2:3]
	v_lshl_add_u64 v[28:29], v[28:29], 0, v[30:31]
	global_load_dword v2, v[28:29], off
	v_add_u32_e32 v28, 0x400, v49
	s_waitcnt vmcnt(30)
	ds_write2_b32 v49, v32, v33 offset1:66
	s_waitcnt vmcnt(28)
	ds_write2_b32 v49, v34, v35 offset0:132 offset1:198
	s_waitcnt vmcnt(26)
	ds_write2_b32 v28, v36, v37 offset0:8 offset1:74
	s_waitcnt vmcnt(24)
	ds_write2_b32 v28, v38, v39 offset0:140 offset1:206
	v_add_u32_e32 v28, 0x800, v49
	s_waitcnt vmcnt(22)
	ds_write2_b32 v28, v40, v41 offset0:16 offset1:82
	s_waitcnt vmcnt(20)
	ds_write2_b32 v28, v42, v43 offset0:148 offset1:214
	v_add_u32_e32 v28, 0xc00, v49
	s_waitcnt vmcnt(18)
	ds_write2_b32 v28, v44, v45 offset0:24 offset1:90
	s_waitcnt vmcnt(16)
	ds_write2_b32 v28, v46, v47 offset0:156 offset1:222
	v_add_u32_e32 v28, 0x1000, v49
	s_waitcnt vmcnt(14)
	ds_write2_b32 v28, v60, v61 offset0:32 offset1:98
	s_waitcnt vmcnt(12)
	ds_write2_b32 v28, v62, v63 offset0:164 offset1:230
	v_add_u32_e32 v28, 0x1400, v49
	s_waitcnt vmcnt(10)
	ds_write2_b32 v28, v64, v65 offset0:40 offset1:106
	s_waitcnt vmcnt(8)
	ds_write2_b32 v28, v66, v67 offset0:172 offset1:238
	v_add_u32_e32 v28, 0x1800, v49
	s_waitcnt vmcnt(6)
	ds_write2_b32 v28, v68, v69 offset0:48 offset1:114
	s_waitcnt vmcnt(4)
	ds_write2_b32 v28, v70, v71 offset0:180 offset1:246
	v_add_u32_e32 v28, 0x1c00, v49
	s_waitcnt vmcnt(2)
	ds_write2_b32 v28, v72, v73 offset0:56 offset1:122
	s_waitcnt vmcnt(0)
	ds_write2_b32 v28, v74, v2 offset0:188 offset1:254
	s_waitcnt lgkmcnt(0)
	ds_read2_b32 v[34:35], v1 offset0:33 offset1:41
	ds_read2_b32 v[36:37], v1 offset1:8
	ds_read2_b32 v[38:39], v1 offset0:66 offset1:74
	ds_read2_b32 v[40:41], v1 offset0:99 offset1:107
	ds_read2_b32 v[42:43], v1 offset0:132 offset1:140
	ds_read2_b32 v[44:45], v1 offset0:165 offset1:173
	ds_read2_b32 v[46:47], v1 offset0:198 offset1:206
	ds_read2_b32 v[60:61], v1 offset0:231 offset1:239
	s_waitcnt lgkmcnt(7)
	s_waitcnt lgkmcnt(6)
	v_cvt_pk_bf16_f32 v30, v36, v34
	s_waitcnt lgkmcnt(5)
	s_waitcnt lgkmcnt(4)
	v_cvt_pk_bf16_f32 v31, v38, v40
	s_waitcnt lgkmcnt(3)
	s_waitcnt lgkmcnt(2)
	v_cvt_pk_bf16_f32 v32, v42, v44
	s_waitcnt lgkmcnt(1)
	s_waitcnt lgkmcnt(0)
	s_lshl_b32 s6, s5, 1
	v_cvt_pk_bf16_f32 v33, v46, v60
	v_or_b32_e32 v2, s4, v50
	v_lshl_add_u64 v[28:29], v[14:15], 0, s[6:7]
	v_mul_u32_u24_e32 v2, 0x1600, v2
	v_lshl_add_u64 v[62:63], v[28:29], 0, v[2:3]
	global_store_dwordx4 v[62:63], v[30:33], off
	s_nop 1
	v_cvt_pk_bf16_f32 v30, v37, v35
	v_cvt_pk_bf16_f32 v31, v39, v41
	v_cvt_pk_bf16_f32 v32, v43, v45
	v_cvt_pk_bf16_f32 v33, v47, v61
	v_or_b32_e32 v2, s4, v51
	v_mul_u32_u24_e32 v2, 0x1600, v2
	v_lshl_add_u64 v[34:35], v[28:29], 0, v[2:3]
	global_store_dwordx4 v[34:35], v[30:33], off
	s_nop 1
	ds_read2_b32 v[34:35], v1 offset0:16 offset1:24
	ds_read2_b32 v[36:37], v1 offset0:49 offset1:57
	ds_read2_b32 v[38:39], v1 offset0:82 offset1:90
	ds_read2_b32 v[40:41], v1 offset0:115 offset1:123
	ds_read2_b32 v[42:43], v1 offset0:148 offset1:156
	ds_read2_b32 v[44:45], v1 offset0:181 offset1:189
	ds_read2_b32 v[46:47], v1 offset0:214 offset1:222
	ds_read2_b32 v[60:61], v1 offset0:247 offset1:255
	s_waitcnt lgkmcnt(7)
	s_waitcnt lgkmcnt(6)
	v_cvt_pk_bf16_f32 v30, v34, v36
	s_waitcnt lgkmcnt(5)
	s_waitcnt lgkmcnt(4)
	v_cvt_pk_bf16_f32 v31, v38, v40
	s_waitcnt lgkmcnt(3)
	s_waitcnt lgkmcnt(2)
	v_cvt_pk_bf16_f32 v32, v42, v44
	s_waitcnt lgkmcnt(1)
	s_waitcnt lgkmcnt(0)
	v_cvt_pk_bf16_f32 v33, v46, v60
	v_or_b32_e32 v2, s4, v52
	v_mul_u32_u24_e32 v2, 0x1600, v2
	v_lshl_add_u64 v[62:63], v[28:29], 0, v[2:3]
	global_store_dwordx4 v[62:63], v[30:33], off
	s_nop 1
	v_cvt_pk_bf16_f32 v30, v35, v37
	v_cvt_pk_bf16_f32 v31, v39, v41
	v_cvt_pk_bf16_f32 v32, v43, v45
	v_cvt_pk_bf16_f32 v33, v47, v61
	v_or_b32_e32 v2, s4, v53
	v_mul_u32_u24_e32 v2, 0x1600, v2
	v_lshl_add_u64 v[28:29], v[28:29], 0, v[2:3]
	global_store_dwordx4 v[28:29], v[30:33], off
	s_nop 1
	s_waitcnt lgkmcnt(0)

.LBB0_145:
	s_andn2_b64 vcc, exec, s[4:5]
	s_cbranch_vccnz .LBB0_147
	s_add_i32 s4, s95, 0x2400
	s_and_b32 s5, s4, 0x7fffffc0
	s_and_b32 s4, s3, 0x3e0
	v_or_b32_e32 v2, s5, v48
	s_lshl_b32 s6, s4, 2
	v_lshl_add_u64 v[28:29], v[16:17], 0, s[6:7]
	v_lshlrev_b64 v[30:31], 12, v[2:3]
	v_lshl_add_u64 v[30:31], v[28:29], 0, v[30:31]
	global_load_dword v32, v[30:31], off
	v_or_b32_e32 v30, 2, v2
	v_mov_b32_e32 v31, v3
	v_lshlrev_b64 v[30:31], 12, v[30:31]
	v_lshl_add_u64 v[30:31], v[28:29], 0, v[30:31]
	global_load_dword v33, v[30:31], off
	v_or_b32_e32 v30, 4, v2
	v_mov_b32_e32 v31, v3
	v_lshlrev_b64 v[30:31], 12, v[30:31]
	v_lshl_add_u64 v[30:31], v[28:29], 0, v[30:31]
	global_load_dword v34, v[30:31], off
	v_or_b32_e32 v30, 6, v2
	v_mov_b32_e32 v31, v3
	v_lshlrev_b64 v[30:31], 12, v[30:31]
	v_lshl_add_u64 v[30:31], v[28:29], 0, v[30:31]
	global_load_dword v35, v[30:31], off
	v_or_b32_e32 v30, 8, v2
	v_mov_b32_e32 v31, v3
	v_lshlrev_b64 v[30:31], 12, v[30:31]
	v_lshl_add_u64 v[30:31], v[28:29], 0, v[30:31]
	global_load_dword v36, v[30:31], off
	v_or_b32_e32 v30, 10, v2
	v_mov_b32_e32 v31, v3
	v_lshlrev_b64 v[30:31], 12, v[30:31]
	v_lshl_add_u64 v[30:31], v[28:29], 0, v[30:31]
	global_load_dword v37, v[30:31], off
	v_or_b32_e32 v30, 12, v2
	v_mov_b32_e32 v31, v3
	v_lshlrev_b64 v[30:31], 12, v[30:31]
	v_lshl_add_u64 v[30:31], v[28:29], 0, v[30:31]
	global_load_dword v38, v[30:31], off
	v_or_b32_e32 v30, 14, v2
	v_mov_b32_e32 v31, v3
	v_lshlrev_b64 v[30:31], 12, v[30:31]
	v_lshl_add_u64 v[30:31], v[28:29], 0, v[30:31]
	global_load_dword v39, v[30:31], off
	v_or_b32_e32 v30, 16, v2
	v_mov_b32_e32 v31, v3
	v_lshlrev_b64 v[30:31], 12, v[30:31]
	v_lshl_add_u64 v[30:31], v[28:29], 0, v[30:31]
	global_load_dword v40, v[30:31], off
	v_or_b32_e32 v30, 18, v2
	v_mov_b32_e32 v31, v3
	v_lshlrev_b64 v[30:31], 12, v[30:31]
	v_lshl_add_u64 v[30:31], v[28:29], 0, v[30:31]
	global_load_dword v41, v[30:31], off
	v_or_b32_e32 v30, 20, v2
	v_mov_b32_e32 v31, v3
	v_lshlrev_b64 v[30:31], 12, v[30:31]
	v_lshl_add_u64 v[30:31], v[28:29], 0, v[30:31]
	global_load_dword v42, v[30:31], off
	v_or_b32_e32 v30, 22, v2
	v_mov_b32_e32 v31, v3
	v_lshlrev_b64 v[30:31], 12, v[30:31]
	v_lshl_add_u64 v[30:31], v[28:29], 0, v[30:31]
	global_load_dword v43, v[30:31], off
	v_or_b32_e32 v30, 24, v2
	v_mov_b32_e32 v31, v3
	v_lshlrev_b64 v[30:31], 12, v[30:31]
	v_lshl_add_u64 v[30:31], v[28:29], 0, v[30:31]
	global_load_dword v44, v[30:31], off
	v_or_b32_e32 v30, 26, v2
	v_mov_b32_e32 v31, v3
	v_lshlrev_b64 v[30:31], 12, v[30:31]
	v_lshl_add_u64 v[30:31], v[28:29], 0, v[30:31]
	global_load_dword v45, v[30:31], off
	v_or_b32_e32 v30, 28, v2
	v_mov_b32_e32 v31, v3
	v_lshlrev_b64 v[30:31], 12, v[30:31]
	v_lshl_add_u64 v[30:31], v[28:29], 0, v[30:31]
	global_load_dword v46, v[30:31], off
	v_or_b32_e32 v30, 30, v2
	v_mov_b32_e32 v31, v3
	v_lshlrev_b64 v[30:31], 12, v[30:31]
	v_lshl_add_u64 v[30:31], v[28:29], 0, v[30:31]
	global_load_dword v47, v[30:31], off
	v_or_b32_e32 v30, 32, v2
	v_mov_b32_e32 v31, v3
	v_lshlrev_b64 v[30:31], 12, v[30:31]
	v_lshl_add_u64 v[30:31], v[28:29], 0, v[30:31]
	global_load_dword v60, v[30:31], off
	v_or_b32_e32 v30, 34, v2
	v_mov_b32_e32 v31, v3
	v_lshlrev_b64 v[30:31], 12, v[30:31]
	v_lshl_add_u64 v[30:31], v[28:29], 0, v[30:31]
	global_load_dword v61, v[30:31], off
	v_or_b32_e32 v30, 36, v2
	v_mov_b32_e32 v31, v3
	v_lshlrev_b64 v[30:31], 12, v[30:31]
	v_lshl_add_u64 v[30:31], v[28:29], 0, v[30:31]
	global_load_dword v62, v[30:31], off
	v_or_b32_e32 v30, 38, v2
	v_mov_b32_e32 v31, v3
	v_lshlrev_b64 v[30:31], 12, v[30:31]
	v_lshl_add_u64 v[30:31], v[28:29], 0, v[30:31]
	global_load_dword v63, v[30:31], off
	v_or_b32_e32 v30, 40, v2
	v_mov_b32_e32 v31, v3
	v_lshlrev_b64 v[30:31], 12, v[30:31]
	v_lshl_add_u64 v[30:31], v[28:29], 0, v[30:31]
	global_load_dword v64, v[30:31], off
	v_or_b32_e32 v30, 42, v2
	v_mov_b32_e32 v31, v3
	v_lshlrev_b64 v[30:31], 12, v[30:31]
	v_lshl_add_u64 v[30:31], v[28:29], 0, v[30:31]
	global_load_dword v65, v[30:31], off
	v_or_b32_e32 v30, 44, v2
	v_mov_b32_e32 v31, v3
	v_lshlrev_b64 v[30:31], 12, v[30:31]
	v_lshl_add_u64 v[30:31], v[28:29], 0, v[30:31]
	global_load_dword v66, v[30:31], off
	v_or_b32_e32 v30, 46, v2
	v_mov_b32_e32 v31, v3
	v_lshlrev_b64 v[30:31], 12, v[30:31]
	v_lshl_add_u64 v[30:31], v[28:29], 0, v[30:31]
	global_load_dword v67, v[30:31], off
	v_or_b32_e32 v30, 48, v2
	v_mov_b32_e32 v31, v3
	v_lshlrev_b64 v[30:31], 12, v[30:31]
	v_lshl_add_u64 v[30:31], v[28:29], 0, v[30:31]
	global_load_dword v68, v[30:31], off
	v_or_b32_e32 v30, 50, v2
	v_mov_b32_e32 v31, v3
	v_lshlrev_b64 v[30:31], 12, v[30:31]
	v_lshl_add_u64 v[30:31], v[28:29], 0, v[30:31]
	global_load_dword v69, v[30:31], off
	v_or_b32_e32 v30, 52, v2
	v_mov_b32_e32 v31, v3
	v_lshlrev_b64 v[30:31], 12, v[30:31]
	v_lshl_add_u64 v[30:31], v[28:29], 0, v[30:31]
	global_load_dword v70, v[30:31], off
	v_or_b32_e32 v30, 54, v2
	v_mov_b32_e32 v31, v3
	v_lshlrev_b64 v[30:31], 12, v[30:31]
	v_lshl_add_u64 v[30:31], v[28:29], 0, v[30:31]
	global_load_dword v71, v[30:31], off
	v_or_b32_e32 v30, 56, v2
	v_mov_b32_e32 v31, v3
	v_lshlrev_b64 v[30:31], 12, v[30:31]
	v_lshl_add_u64 v[30:31], v[28:29], 0, v[30:31]
	global_load_dword v72, v[30:31], off
	v_or_b32_e32 v30, 58, v2
	v_mov_b32_e32 v31, v3
	v_lshlrev_b64 v[30:31], 12, v[30:31]
	v_lshl_add_u64 v[30:31], v[28:29], 0, v[30:31]
	global_load_dword v73, v[30:31], off
	v_or_b32_e32 v30, 60, v2
	v_mov_b32_e32 v31, v3
	v_lshlrev_b64 v[30:31], 12, v[30:31]
	v_lshl_add_u64 v[30:31], v[28:29], 0, v[30:31]
	v_or_b32_e32 v2, 62, v2
	global_load_dword v74, v[30:31], off
	v_lshlrev_b64 v[30:31], 12, v[2:3]
	v_lshl_add_u64 v[28:29], v[28:29], 0, v[30:31]
	global_load_dword v2, v[28:29], off
	v_add_u32_e32 v28, 0x400, v49
	s_waitcnt vmcnt(30)
	ds_write2_b32 v49, v32, v33 offset1:66
	s_waitcnt vmcnt(28)
	ds_write2_b32 v49, v34, v35 offset0:132 offset1:198
	s_waitcnt vmcnt(26)
	ds_write2_b32 v28, v36, v37 offset0:8 offset1:74
	s_waitcnt vmcnt(24)
	ds_write2_b32 v28, v38, v39 offset0:140 offset1:206
	v_add_u32_e32 v28, 0x800, v49
	s_waitcnt vmcnt(22)
	ds_write2_b32 v28, v40, v41 offset0:16 offset1:82
	s_waitcnt vmcnt(20)
	ds_write2_b32 v28, v42, v43 offset0:148 offset1:214
	v_add_u32_e32 v28, 0xc00, v49
	s_waitcnt vmcnt(18)
	ds_write2_b32 v28, v44, v45 offset0:24 offset1:90
	s_waitcnt vmcnt(16)
	ds_write2_b32 v28, v46, v47 offset0:156 offset1:222
	v_add_u32_e32 v28, 0x1000, v49
	s_waitcnt vmcnt(14)
	ds_write2_b32 v28, v60, v61 offset0:32 offset1:98
	s_waitcnt vmcnt(12)
	ds_write2_b32 v28, v62, v63 offset0:164 offset1:230
	v_add_u32_e32 v28, 0x1400, v49
	s_waitcnt vmcnt(10)
	ds_write2_b32 v28, v64, v65 offset0:40 offset1:106
	s_waitcnt vmcnt(8)
	ds_write2_b32 v28, v66, v67 offset0:172 offset1:238
	v_add_u32_e32 v28, 0x1800, v49
	s_waitcnt vmcnt(6)
	ds_write2_b32 v28, v68, v69 offset0:48 offset1:114
	s_waitcnt vmcnt(4)
	ds_write2_b32 v28, v70, v71 offset0:180 offset1:246
	v_add_u32_e32 v28, 0x1c00, v49
	s_waitcnt vmcnt(2)
	ds_write2_b32 v28, v72, v73 offset0:56 offset1:122
	s_waitcnt vmcnt(0)
	ds_write2_b32 v28, v74, v2 offset0:188 offset1:254
	s_waitcnt lgkmcnt(0)
	ds_read2_b32 v[34:35], v1 offset0:33 offset1:41
	ds_read2_b32 v[36:37], v1 offset1:8
	ds_read2_b32 v[38:39], v1 offset0:66 offset1:74
	ds_read2_b32 v[40:41], v1 offset0:99 offset1:107
	ds_read2_b32 v[42:43], v1 offset0:132 offset1:140
	ds_read2_b32 v[44:45], v1 offset0:165 offset1:173
	ds_read2_b32 v[46:47], v1 offset0:198 offset1:206
	ds_read2_b32 v[60:61], v1 offset0:231 offset1:239
	s_waitcnt lgkmcnt(7)
	s_waitcnt lgkmcnt(6)
	v_cvt_pk_bf16_f32 v30, v36, v34
	s_waitcnt lgkmcnt(5)
	s_waitcnt lgkmcnt(4)
	v_cvt_pk_bf16_f32 v31, v38, v40
	s_waitcnt lgkmcnt(3)
	s_waitcnt lgkmcnt(2)
	v_cvt_pk_bf16_f32 v32, v42, v44
	s_waitcnt lgkmcnt(1)
	s_waitcnt lgkmcnt(0)
	s_lshl_b32 s6, s5, 1
	v_cvt_pk_bf16_f32 v33, v46, v60
	v_or_b32_e32 v2, s4, v50
	v_lshl_add_u64 v[28:29], v[18:19], 0, s[6:7]
	v_mul_u32_u24_e32 v2, 0x1600, v2
	v_lshl_add_u64 v[62:63], v[28:29], 0, v[2:3]
	global_store_dwordx4 v[62:63], v[30:33], off
	s_nop 1
	v_cvt_pk_bf16_f32 v30, v37, v35
	v_cvt_pk_bf16_f32 v31, v39, v41
	v_cvt_pk_bf16_f32 v32, v43, v45
	v_cvt_pk_bf16_f32 v33, v47, v61
	v_or_b32_e32 v2, s4, v51
	v_mul_u32_u24_e32 v2, 0x1600, v2
	v_lshl_add_u64 v[34:35], v[28:29], 0, v[2:3]
	global_store_dwordx4 v[34:35], v[30:33], off
	s_nop 1
	ds_read2_b32 v[34:35], v1 offset0:16 offset1:24
	ds_read2_b32 v[36:37], v1 offset0:49 offset1:57
	ds_read2_b32 v[38:39], v1 offset0:82 offset1:90
	ds_read2_b32 v[40:41], v1 offset0:115 offset1:123
	ds_read2_b32 v[42:43], v1 offset0:148 offset1:156
	ds_read2_b32 v[44:45], v1 offset0:181 offset1:189
	ds_read2_b32 v[46:47], v1 offset0:214 offset1:222
	ds_read2_b32 v[60:61], v1 offset0:247 offset1:255
	s_waitcnt lgkmcnt(7)
	s_waitcnt lgkmcnt(6)
	v_cvt_pk_bf16_f32 v30, v34, v36
	s_waitcnt lgkmcnt(5)
	s_waitcnt lgkmcnt(4)
	v_cvt_pk_bf16_f32 v31, v38, v40
	s_waitcnt lgkmcnt(3)
	s_waitcnt lgkmcnt(2)
	v_cvt_pk_bf16_f32 v32, v42, v44
	s_waitcnt lgkmcnt(1)
	s_waitcnt lgkmcnt(0)
	v_cvt_pk_bf16_f32 v33, v46, v60
	v_or_b32_e32 v2, s4, v52
	v_mul_u32_u24_e32 v2, 0x1600, v2
	v_lshl_add_u64 v[62:63], v[28:29], 0, v[2:3]
	global_store_dwordx4 v[62:63], v[30:33], off
	s_nop 1
	v_cvt_pk_bf16_f32 v30, v35, v37
	v_cvt_pk_bf16_f32 v31, v39, v41
	v_cvt_pk_bf16_f32 v32, v43, v45
	v_cvt_pk_bf16_f32 v33, v47, v61
	v_or_b32_e32 v2, s4, v53
	v_mul_u32_u24_e32 v2, 0x1600, v2
	v_lshl_add_u64 v[28:29], v[28:29], 0, v[2:3]
	global_store_dwordx4 v[28:29], v[30:33], off
	s_nop 1
	s_waitcnt lgkmcnt(0)

.LBB0_153:
	s_lshl_b32 s4, s6, 6
	s_and_b32 s4, s4, 0x7fc0
	v_or_b32_e32 v2, s4, v48
	s_lshl_b32 s6, s33, 2
	v_lshl_add_u64 v[28:29], v[20:21], 0, s[6:7]
	v_mul_u32_u24_e32 v2, 0x5800, v2
	v_lshl_add_u64 v[28:29], v[28:29], 0, v[2:3]
	v_add_co_u32_e32 v30, vcc, 0xb000, v28
	global_load_dword v2, v[28:29], off
	s_nop 0
	v_addc_co_u32_e32 v31, vcc, 0, v29, vcc
	global_load_dword v32, v[30:31], off
	v_add_co_u32_e32 v30, vcc, 0x16000, v28
	s_lshl_b32 s6, s4, 1
	s_nop 0
	v_addc_co_u32_e32 v31, vcc, 0, v29, vcc
	global_load_dword v33, v[30:31], off
	v_add_co_u32_e32 v30, vcc, 0x21000, v28
	s_nop 1
	v_addc_co_u32_e32 v31, vcc, 0, v29, vcc
	global_load_dword v34, v[30:31], off
	v_add_co_u32_e32 v30, vcc, 0x2c000, v28
	s_nop 1
	v_addc_co_u32_e32 v31, vcc, 0, v29, vcc
	global_load_dword v35, v[30:31], off
	v_add_co_u32_e32 v30, vcc, 0x37000, v28
	s_nop 1
	v_addc_co_u32_e32 v31, vcc, 0, v29, vcc
	global_load_dword v36, v[30:31], off
	v_add_co_u32_e32 v30, vcc, 0x42000, v28
	s_nop 1
	v_addc_co_u32_e32 v31, vcc, 0, v29, vcc
	global_load_dword v37, v[30:31], off
	v_add_co_u32_e32 v30, vcc, s11, v28
	s_nop 1
	v_addc_co_u32_e32 v31, vcc, 0, v29, vcc
	global_load_dword v38, v[30:31], off
	v_add_co_u32_e32 v30, vcc, 0x58000, v28
	s_nop 1
	v_addc_co_u32_e32 v31, vcc, 0, v29, vcc
	global_load_dword v39, v[30:31], off
	v_add_co_u32_e32 v30, vcc, 0x63000, v28
	s_nop 1
	v_addc_co_u32_e32 v31, vcc, 0, v29, vcc
	global_load_dword v40, v[30:31], off
	v_add_co_u32_e32 v30, vcc, 0x6e000, v28
	s_nop 1
	v_addc_co_u32_e32 v31, vcc, 0, v29, vcc
	global_load_dword v41, v[30:31], off
	v_add_co_u32_e32 v30, vcc, 0x79000, v28
	s_nop 1
	v_addc_co_u32_e32 v31, vcc, 0, v29, vcc
	global_load_dword v42, v[30:31], off
	v_add_co_u32_e32 v30, vcc, 0x84000, v28
	s_nop 1
	v_addc_co_u32_e32 v31, vcc, 0, v29, vcc
	global_load_dword v43, v[30:31], off
	v_add_co_u32_e32 v30, vcc, 0x8f000, v28
	s_nop 1
	v_addc_co_u32_e32 v31, vcc, 0, v29, vcc
	global_load_dword v44, v[30:31], off
	v_add_co_u32_e32 v30, vcc, s12, v28
	s_nop 1
	v_addc_co_u32_e32 v31, vcc, 0, v29, vcc
	global_load_dword v45, v[30:31], off
	v_add_co_u32_e32 v30, vcc, 0xa5000, v28
	s_nop 1
	v_addc_co_u32_e32 v31, vcc, 0, v29, vcc
	global_load_dword v46, v[30:31], off
	v_add_co_u32_e32 v30, vcc, 0xb0000, v28
	s_nop 1
	v_addc_co_u32_e32 v31, vcc, 0, v29, vcc
	global_load_dword v47, v[30:31], off
	v_add_co_u32_e32 v30, vcc, 0xbb000, v28
	s_nop 1
	v_addc_co_u32_e32 v31, vcc, 0, v29, vcc
	global_load_dword v60, v[30:31], off
	v_add_co_u32_e32 v30, vcc, 0xc6000, v28
	s_nop 1
	v_addc_co_u32_e32 v31, vcc, 0, v29, vcc
	global_load_dword v61, v[30:31], off
	v_add_co_u32_e32 v30, vcc, 0xd1000, v28
	s_nop 1
	v_addc_co_u32_e32 v31, vcc, 0, v29, vcc
	global_load_dword v62, v[30:31], off
	v_add_co_u32_e32 v30, vcc, 0xdc000, v28
	s_nop 1
	v_addc_co_u32_e32 v31, vcc, 0, v29, vcc
	global_load_dword v63, v[30:31], off
	v_add_co_u32_e32 v30, vcc, 0xe7000, v28
	s_nop 1
	v_addc_co_u32_e32 v31, vcc, 0, v29, vcc
	global_load_dword v64, v[30:31], off
	v_add_co_u32_e32 v30, vcc, 0xf2000, v28
	s_nop 1
	v_addc_co_u32_e32 v31, vcc, 0, v29, vcc
	global_load_dword v65, v[30:31], off
	v_add_co_u32_e32 v30, vcc, 0xfd000, v28
	s_nop 1
	v_addc_co_u32_e32 v31, vcc, 0, v29, vcc
	global_load_dword v66, v[30:31], off
	v_add_co_u32_e32 v30, vcc, 0x108000, v28
	s_nop 1
	v_addc_co_u32_e32 v31, vcc, 0, v29, vcc
	global_load_dword v67, v[30:31], off
	v_add_co_u32_e32 v30, vcc, 0x113000, v28
	s_nop 1
	v_addc_co_u32_e32 v31, vcc, 0, v29, vcc
	global_load_dword v68, v[30:31], off
	v_add_co_u32_e32 v30, vcc, 0x11e000, v28
	s_nop 1
	v_addc_co_u32_e32 v31, vcc, 0, v29, vcc
	global_load_dword v69, v[30:31], off
	v_add_co_u32_e32 v30, vcc, 0x129000, v28
	s_nop 1
	v_addc_co_u32_e32 v31, vcc, 0, v29, vcc
	global_load_dword v70, v[30:31], off
	v_add_co_u32_e32 v30, vcc, 0x134000, v28
	s_nop 1
	v_addc_co_u32_e32 v31, vcc, 0, v29, vcc
	global_load_dword v71, v[30:31], off
	v_add_co_u32_e32 v30, vcc, 0x13f000, v28
	s_nop 1
	v_addc_co_u32_e32 v31, vcc, 0, v29, vcc
	global_load_dword v72, v[30:31], off
	v_add_co_u32_e32 v30, vcc, 0x14a000, v28
	s_nop 1
	v_addc_co_u32_e32 v31, vcc, 0, v29, vcc
	v_add_co_u32_e32 v28, vcc, 0x155000, v28
	global_load_dword v30, v[30:31], off
	s_nop 0
	v_addc_co_u32_e32 v29, vcc, 0, v29, vcc
	global_load_dword v28, v[28:29], off
	s_waitcnt vmcnt(30)
	ds_write2_b32 v49, v2, v32 offset1:66
	s_waitcnt vmcnt(28)
	ds_write2_b32 v49, v33, v34 offset0:132 offset1:198
	v_add_u32_e32 v2, 0x400, v49
	s_waitcnt vmcnt(26)
	ds_write2_b32 v2, v35, v36 offset0:8 offset1:74
	s_waitcnt vmcnt(24)
	ds_write2_b32 v2, v37, v38 offset0:140 offset1:206
	v_add_u32_e32 v2, 0x800, v49
	s_waitcnt vmcnt(22)
	ds_write2_b32 v2, v39, v40 offset0:16 offset1:82
	s_waitcnt vmcnt(20)
	ds_write2_b32 v2, v41, v42 offset0:148 offset1:214
	v_add_u32_e32 v2, 0xc00, v49
	s_waitcnt vmcnt(18)
	ds_write2_b32 v2, v43, v44 offset0:24 offset1:90
	s_waitcnt vmcnt(16)
	ds_write2_b32 v2, v45, v46 offset0:156 offset1:222
	v_add_u32_e32 v2, 0x1000, v49
	s_waitcnt vmcnt(14)
	ds_write2_b32 v2, v47, v60 offset0:32 offset1:98
	s_waitcnt vmcnt(12)
	ds_write2_b32 v2, v61, v62 offset0:164 offset1:230
	v_add_u32_e32 v2, 0x1400, v49
	s_waitcnt vmcnt(10)
	ds_write2_b32 v2, v63, v64 offset0:40 offset1:106
	s_waitcnt vmcnt(8)
	ds_write2_b32 v2, v65, v66 offset0:172 offset1:238
	v_add_u32_e32 v2, 0x1800, v49
	s_waitcnt vmcnt(6)
	ds_write2_b32 v2, v67, v68 offset0:48 offset1:114
	s_waitcnt vmcnt(4)
	ds_write2_b32 v2, v69, v70 offset0:180 offset1:246
	v_add_u32_e32 v2, 0x1c00, v49
	s_waitcnt vmcnt(2)
	ds_write2_b32 v2, v71, v72 offset0:56 offset1:122
	s_waitcnt vmcnt(0)
	ds_write2_b32 v2, v30, v28 offset0:188 offset1:254
	s_waitcnt lgkmcnt(0)
	ds_read2_b32 v[34:35], v1 offset0:33 offset1:41
	ds_read2_b32 v[36:37], v1 offset1:8
	ds_read2_b32 v[38:39], v1 offset0:66 offset1:74
	ds_read2_b32 v[40:41], v1 offset0:99 offset1:107
	ds_read2_b32 v[42:43], v1 offset0:132 offset1:140
	ds_read2_b32 v[44:45], v1 offset0:165 offset1:173
	ds_read2_b32 v[46:47], v1 offset0:198 offset1:206
	ds_read2_b32 v[60:61], v1 offset0:231 offset1:239
	s_waitcnt lgkmcnt(7)
	s_waitcnt lgkmcnt(6)
	v_cvt_pk_bf16_f32 v30, v36, v34
	s_waitcnt lgkmcnt(5)
	s_waitcnt lgkmcnt(4)
	v_cvt_pk_bf16_f32 v31, v38, v40
	s_waitcnt lgkmcnt(3)
	s_waitcnt lgkmcnt(2)
	v_cvt_pk_bf16_f32 v32, v42, v44
	s_waitcnt lgkmcnt(1)
	s_waitcnt lgkmcnt(0)
	v_cvt_pk_bf16_f32 v33, v46, v60
	v_add_u32_e32 v2, s68, v50
	v_lshl_add_u64 v[28:29], v[22:23], 0, s[6:7]
	v_lshlrev_b64 v[62:63], 11, v[2:3]
	v_lshl_add_u64 v[62:63], v[28:29], 0, v[62:63]
	global_store_dwordx4 v[62:63], v[30:33], off
	s_nop 1
	v_cvt_pk_bf16_f32 v30, v37, v35
	v_cvt_pk_bf16_f32 v31, v39, v41
	v_cvt_pk_bf16_f32 v32, v43, v45
	v_cvt_pk_bf16_f32 v33, v47, v61
	v_add_u32_e32 v2, s68, v51
	v_lshlrev_b64 v[34:35], 11, v[2:3]
	v_lshl_add_u64 v[34:35], v[28:29], 0, v[34:35]
	global_store_dwordx4 v[34:35], v[30:33], off
	s_nop 1
	ds_read2_b32 v[34:35], v1 offset0:49 offset1:57
	ds_read2_b32 v[36:37], v1 offset0:16 offset1:24
	ds_read2_b32 v[38:39], v1 offset0:82 offset1:90
	ds_read2_b32 v[40:41], v1 offset0:115 offset1:123
	ds_read2_b32 v[42:43], v1 offset0:148 offset1:156
	ds_read2_b32 v[44:45], v1 offset0:181 offset1:189
	ds_read2_b32 v[46:47], v1 offset0:214 offset1:222
	ds_read2_b32 v[60:61], v1 offset0:247 offset1:255
	s_waitcnt lgkmcnt(7)
	s_waitcnt lgkmcnt(6)
	v_cvt_pk_bf16_f32 v30, v36, v34
	s_waitcnt lgkmcnt(5)
	s_waitcnt lgkmcnt(4)
	v_cvt_pk_bf16_f32 v31, v38, v40
	s_waitcnt lgkmcnt(3)
	s_waitcnt lgkmcnt(2)
	v_cvt_pk_bf16_f32 v32, v42, v44
	s_waitcnt lgkmcnt(1)
	s_waitcnt lgkmcnt(0)
	v_cvt_pk_bf16_f32 v33, v46, v60
	v_add_u32_e32 v2, s68, v52
	v_lshlrev_b64 v[62:63], 11, v[2:3]
	v_lshl_add_u64 v[62:63], v[28:29], 0, v[62:63]
	global_store_dwordx4 v[62:63], v[30:33], off
	s_nop 1
	v_cvt_pk_bf16_f32 v30, v37, v35
	v_cvt_pk_bf16_f32 v31, v39, v41
	v_cvt_pk_bf16_f32 v32, v43, v45
	v_cvt_pk_bf16_f32 v33, v47, v61
	v_add_u32_e32 v2, s68, v53
	v_lshlrev_b64 v[34:35], 11, v[2:3]
	v_lshl_add_u64 v[28:29], v[28:29], 0, v[34:35]
	global_store_dwordx4 v[28:29], v[30:33], off
	s_nop 1
	s_waitcnt lgkmcnt(0)
